# w_in and MLP-up GEMM: first two counted waits of a unit that follows an epilogue relaxed to vmcnt(24) so the 16 epilogue stores need not be acknowledged before the next K-loop starts
# baseline (speedup 1.0000x reference)
; #define PG8_STAGE(bufoff, gbase, voff) do { _Pragma("unroll") for (int _i = 0; _i < 2; ++_i) \
;         __builtin_amdgcn_global_load_lds((const unsigned*)((const char*)(gbase) + (voff)[_i]), (PG8_LAS unsigned*)(lds + (bufoff) + ldsw + _i * 8192), 16, 0, 0); } while (0)
; #define PG8_WAIT_V(n) asm volatile("s_waitcnt vmcnt(" #n ")" ::: "memory")
; #define PG8_BAR __builtin_amdgcn_s_barrier()
; template <class Epi, class Sched, bool ALIGN_EPI = false, bool SP2 = false>
; __device__ __forceinline__ void gemm_phase(PG8_LAS unsigned char* lds, const Gemm g, const Sched& S, const Epi& E) {
;     ...
;     f32x4 acc[2][2][4][2];
; #pragma unroll
;     for (int a = 0; a < 2; ++a)
; #pragma unroll
;         for (int b = 0; b < 2; ++b)
; #pragma unroll
;             for (int m = 0; m < 4; ++m)
; #pragma unroll
;                 for (int n = 0; n < 2; ++n) acc[a][b][m][n] = (f32x4){0.f, 0.f, 0.f, 0.f};
;     bf16x8 At[4][2], B0[2][2], B1[2][2];
;     const char* cA = (const char*)g.A + (size_t)cur.pm * tstep; const char* cB = (const char*)g.Bt + (size_t)cur.pn * tstep;
;     S.a_ready(cur);
;     if constexpr (SP2) {
;         PG8_STAGE(PG8_SB(0, 0), cB, voffB); PG8_STAGE(PG8_SB(0, 1), cB + hstepB, voffB); PG8_STAGE(PG8_SA(0, 0), cA, voffA); PG8_STAGE(PG8_SA(0, 1), cA + hstep, voffA);
;         if (wr == 1) PG8_BAR;
;         PG8_WAIT_V(2); PG8_BAR;
;         PG8_STAGE(PG8_SB(1, 0), cB + kstep, voffB); PG8_STAGE(PG8_SA(1, 0), cA + kstep, voffA); PG8_STAGE(PG8_SB(1, 1), cB + hstepB + kstep, voffB);
;         PG8_WAIT_V(6); PG8_BAR;
;     } else {
;         PG8_STAGE(PG8_SB(0, 0), cB, voffB); PG8_STAGE(PG8_SA(0, 0), cA, voffA); PG8_STAGE(PG8_SB(0, 1), cB + hstepB, voffB); PG8_STAGE(PG8_SA(0, 1), cA + hstep, voffA);
;         if (wr == 1) PG8_BAR;
;         PG8_WAIT_V(4); PG8_BAR;
;         PG8_STAGE(PG8_SB(1, 0), cB + kstep, voffB); PG8_STAGE(PG8_SA(1, 0), cA + kstep, voffA); PG8_STAGE(PG8_SB(1, 1), cB + hstepB + kstep, voffB);
;         PG8_WAIT_V(6); PG8_BAR;
;     }
.LBB0_165:
	v_readlane_b32 s46, v254, 24
	v_mov_b32_e32 v133, v191
	v_readlane_b32 s47, v254, 25
	v_mov_b32_e32 v137, v191
	v_readlane_b32 s70, v254, 20
	v_lshl_add_u64 v[8:9], s[46:47], 0, v[132:133]
	v_lshl_add_u64 v[10:11], s[46:47], 0, v[136:137]
	v_mov_b32_e32 v131, v191
	v_readlane_b32 s71, v254, 21
	s_add_i32 m0, s1, 0x18000
	v_lshl_add_u64 v[8:9], v[8:9], 0, s[60:61]
	v_lshl_add_u64 v[12:13], s[70:71], 0, v[130:131]
	v_mov_b32_e32 v135, v191
	s_waitcnt vmcnt(2)
	s_barrier
	global_load_lds_dwordx4 v[8:9], off
	v_lshl_add_u64 v[8:9], v[10:11], 0, s[60:61]
	s_add_i32 m0, s1, 0x1a000
	s_add_i32 s66, s1, 0x8000
	v_lshl_add_u64 v[14:15], s[70:71], 0, v[134:135]
	global_load_lds_dwordx4 v[8:9], off
	v_lshl_add_u64 v[8:9], v[12:13], 0, s[60:61]
	s_mov_b32 m0, s66
	s_add_i32 s67, s1, 0xa000
	v_readlane_b32 s6, v254, 26
	global_load_lds_dwordx4 v[8:9], off
	v_lshl_add_u64 v[8:9], v[14:15], 0, s[60:61]
	s_mov_b32 m0, s67
	v_readlane_b32 s7, v254, 27
	global_load_lds_dwordx4 v[8:9], off
	s_add_i32 m0, s1, 0x1c000
	v_lshl_add_u64 v[8:9], s[6:7], 0, v[132:133]
	global_load_lds_dwordx4 v[8:9], off
	v_lshl_add_u64 v[8:9], s[6:7], 0, v[136:137]
	s_add_i32 m0, s1, 0x1e000
	v_lshrrev_b32_e32 v17, 1, v26
	global_load_lds_dwordx4 v[8:9], off
	v_and_b32_e32 v138, 24, v17
	v_and_b32_e32 v16, 15, v26
	v_lshlrev_b32_e32 v17, 1, v138
	v_lshlrev_b32_e32 v8, 15, v2
	v_lshl_or_b32 v1, s5, 6, v16
	v_lshl_or_b32 v17, v16, 6, v17
	v_lshlrev_b32_e32 v16, 2, v16
	v_and_b32_e32 v8, 0xffff0000, v8
	s_and_b32 s59, s4, 3
	s_lshl_b32 s4, s5, 13
	v_and_b32_e32 v18, 32, v16
	v_lshl_add_u32 v3, v3, 12, v8
	v_and_b32_e32 v2, 1, v2
	v_bitop3_b32 v19, v17, s4, v18 bitop3:0xde
	s_lshl_b32 s4, s59, 12
	v_lshl_or_b32 v2, v2, 6, v3
	s_cmpk_lt_u32 s36, 0x100
	v_lshl_add_u32 v140, v4, 1, v2
	v_lshlrev_b32_e32 v2, 15, v5
	v_bitop3_b32 v139, v17, s4, v18 bitop3:0xde
	s_cselect_b64 s[54:55], -1, 0
	s_lshl_b32 s4, s5, 8
	v_and_b32_e32 v2, 0xffff0000, v2
	s_add_i32 s4, s4, 0
	v_lshl_add_u32 v2, v6, 12, v2
	v_and_b32_e32 v3, 1, v5
	s_waitcnt vmcnt(6)
	s_add_i32 s4, s4, 0x20000
	v_lshl_or_b32 v2, v3, 6, v2
	v_add_u32_e32 v164, s4, v16
	v_lshl_add_u32 v142, v7, 1, v2
	v_mov_b32_e32 v2, 0
	v_readlane_b32 s4, v254, 16
	s_lshl_b32 s74, s59, 6
	v_mov_b32_e32 v141, v191
	v_mov_b32_e32 v143, v191
	s_mov_b32 s87, 0
	v_add_u32_e32 v165, 0, v19
	v_readlane_b32 s75, v253, 41
	s_mov_b32 s86, s4
	v_mov_b32_e32 v3, v2
	v_mov_b32_e32 v4, v2
	v_mov_b32_e32 v5, v2
	v_mov_b32_e32 v6, v2
	v_mov_b32_e32 v7, v2
	v_mov_b32_e32 v8, v2
	v_mov_b32_e32 v9, v2
	v_mov_b32_e32 v10, v2
	v_mov_b32_e32 v11, v2
	v_mov_b32_e32 v12, v2
	v_mov_b32_e32 v13, v2
	v_mov_b32_e32 v14, v2
	v_mov_b32_e32 v15, v2
	v_mov_b32_e32 v16, v2
	v_mov_b32_e32 v17, v2
	v_mov_b32_e32 v18, v2
	v_mov_b32_e32 v19, v2
	v_mov_b32_e32 v20, v2
	v_mov_b32_e32 v21, v2
	v_mov_b32_e32 v22, v2
	v_mov_b32_e32 v23, v2
	v_mov_b32_e32 v24, v2
	v_mov_b32_e32 v25, v2
	v_mov_b32_e32 v26, v2
	v_mov_b32_e32 v27, v2
	v_mov_b32_e32 v28, v2
	v_mov_b32_e32 v29, v2
	v_mov_b32_e32 v30, v2
	v_mov_b32_e32 v31, v2
	v_mov_b32_e32 v32, v2
	v_mov_b32_e32 v33, v2
	v_mov_b32_e32 v34, v2
	s_waitcnt lgkmcnt(0)
	v_mov_b32_e32 v35, v2
	v_mov_b32_e32 v36, v2
	v_mov_b32_e32 v37, v2
	v_mov_b32_e32 v38, v2
	v_mov_b32_e32 v39, v2
	v_mov_b32_e32 v40, v2
	v_mov_b32_e32 v41, v2
	v_mov_b32_e32 v42, v2
	v_mov_b32_e32 v43, v2
	v_mov_b32_e32 v44, v2
	v_mov_b32_e32 v45, v2
	v_mov_b32_e32 v46, v2
	v_mov_b32_e32 v47, v2
	v_mov_b32_e32 v48, v2
	v_mov_b32_e32 v49, v2
	v_mov_b32_e32 v50, v2
	v_mov_b32_e32 v51, v2
	v_mov_b32_e32 v52, v2
	v_mov_b32_e32 v53, v2
	v_mov_b32_e32 v54, v2
	v_mov_b32_e32 v55, v2
	v_mov_b32_e32 v56, v2
	v_mov_b32_e32 v57, v2
	v_mov_b32_e32 v58, v2
	v_mov_b32_e32 v59, v2
	v_mov_b32_e32 v60, v2
	v_mov_b32_e32 v61, v2
	v_mov_b32_e32 v62, v2
	v_mov_b32_e32 v63, v2
	v_mov_b32_e32 v64, v2
	v_mov_b32_e32 v65, v2
	v_mov_b32_e32 v66, v2
	v_mov_b32_e32 v67, v2
	v_mov_b32_e32 v68, v2
	v_mov_b32_e32 v69, v2
	v_mov_b32_e32 v70, v2
	v_mov_b32_e32 v71, v2
	v_mov_b32_e32 v72, v2
	v_mov_b32_e32 v73, v2
	v_mov_b32_e32 v74, v2
	v_mov_b32_e32 v75, v2
	v_mov_b32_e32 v76, v2
	v_mov_b32_e32 v77, v2
	v_mov_b32_e32 v78, v2
	v_mov_b32_e32 v79, v2
	v_mov_b32_e32 v80, v2
	v_mov_b32_e32 v81, v2
	v_mov_b32_e32 v82, v2
	v_mov_b32_e32 v83, v2
	v_mov_b32_e32 v84, v2
	v_mov_b32_e32 v85, v2
	v_mov_b32_e32 v86, v2
	v_mov_b32_e32 v87, v2
	v_mov_b32_e32 v88, v2
	v_mov_b32_e32 v89, v2
	v_mov_b32_e32 v90, v2
	v_mov_b32_e32 v91, v2
	v_mov_b32_e32 v92, v2
	v_mov_b32_e32 v93, v2
	v_mov_b32_e32 v94, v2
	v_mov_b32_e32 v95, v2
	v_mov_b32_e32 v96, v2
	v_mov_b32_e32 v97, v2
	v_mov_b32_e32 v98, v2
	v_mov_b32_e32 v99, v2
	v_mov_b32_e32 v100, v2
	v_mov_b32_e32 v101, v2
	v_mov_b32_e32 v102, v2
	v_mov_b32_e32 v103, v2
	v_mov_b32_e32 v104, v2
	v_mov_b32_e32 v105, v2
	v_mov_b32_e32 v106, v2
	v_mov_b32_e32 v107, v2
	v_mov_b32_e32 v108, v2
	v_mov_b32_e32 v109, v2
	v_mov_b32_e32 v110, v2
	v_mov_b32_e32 v111, v2
	v_mov_b32_e32 v112, v2
	v_mov_b32_e32 v113, v2
	v_mov_b32_e32 v114, v2
	v_mov_b32_e32 v115, v2
	v_mov_b32_e32 v116, v2
	v_mov_b32_e32 v117, v2
	v_mov_b32_e32 v118, v2
	v_mov_b32_e32 v119, v2
	v_mov_b32_e32 v120, v2
	v_mov_b32_e32 v121, v2
	v_mov_b32_e32 v122, v2
	v_mov_b32_e32 v123, v2
	v_mov_b32_e32 v124, v2
	v_mov_b32_e32 v125, v2
	v_mov_b32_e32 v126, v2
	v_mov_b32_e32 v127, v2
	v_mov_b32_e32 v128, v2
	v_mov_b32_e32 v129, v2
	s_barrier
	v_readlane_b32 s5, v254, 17
	s_mov_b32 s101, 0
	s_branch .LBB0_167
; #define PG8_BAR __builtin_amdgcn_s_barrier()
; template <class Epi, class Sched, bool ALIGN_EPI = false, bool SP2 = false>
; __device__ __forceinline__ void gemm_phase(PG8_LAS unsigned char* lds, const Gemm g, const Sched& S, const Epi& E) {
;     ...
; #pragma unroll
;         for (int a = 0; a < 2; ++a)
; #pragma unroll
;             for (int b = 0; b < 2; ++b)
; #pragma unroll
;                 for (int m = 0; m < 4; ++m)
; #pragma unroll
;                     for (int n = 0; n < 2; ++n) acc[a][b][m][n] = (f32x4){0.f, 0.f, 0.f, 0.f};
;         cur = nxt; cA = nA; cB = nB; ++ui;
;         if constexpr (ALIGN_EPI) { if (wr == 1) PG8_BAR; }
.LBB0_166:
	s_mov_b32 s101, 1
	v_mov_b32_e32 v2, 0
	s_mov_b32 s75, s62
	s_mov_b32 s86, s68
	v_mov_b32_e32 v3, v2
	v_mov_b32_e32 v4, v2
	v_mov_b32_e32 v5, v2
	v_mov_b32_e32 v6, v2
	v_mov_b32_e32 v7, v2
	v_mov_b32_e32 v8, v2
	v_mov_b32_e32 v9, v2
	v_mov_b32_e32 v10, v2
	v_mov_b32_e32 v11, v2
	v_mov_b32_e32 v12, v2
	v_mov_b32_e32 v13, v2
	v_mov_b32_e32 v14, v2
	v_mov_b32_e32 v15, v2
	v_mov_b32_e32 v16, v2
	v_mov_b32_e32 v17, v2
	v_mov_b32_e32 v18, v2
	v_mov_b32_e32 v19, v2
	v_mov_b32_e32 v20, v2
	v_mov_b32_e32 v21, v2
	v_mov_b32_e32 v22, v2
	v_mov_b32_e32 v23, v2
	v_mov_b32_e32 v24, v2
	v_mov_b32_e32 v25, v2
	v_mov_b32_e32 v26, v2
	v_mov_b32_e32 v27, v2
	v_mov_b32_e32 v28, v2
	v_mov_b32_e32 v29, v2
	v_mov_b32_e32 v30, v2
	v_mov_b32_e32 v31, v2
	v_mov_b32_e32 v32, v2
	v_mov_b32_e32 v33, v2
	v_mov_b32_e32 v34, v2
	v_mov_b32_e32 v35, v2
	v_mov_b32_e32 v36, v2
	v_mov_b32_e32 v37, v2
	v_mov_b32_e32 v38, v2
	v_mov_b32_e32 v39, v2
	v_mov_b32_e32 v40, v2
	v_mov_b32_e32 v41, v2
	v_mov_b32_e32 v42, v2
	v_mov_b32_e32 v43, v2
	v_mov_b32_e32 v44, v2
	v_mov_b32_e32 v45, v2
	v_mov_b32_e32 v46, v2
	v_mov_b32_e32 v47, v2
	v_mov_b32_e32 v48, v2
	v_mov_b32_e32 v49, v2
	v_mov_b32_e32 v50, v2
	v_mov_b32_e32 v51, v2
	v_mov_b32_e32 v52, v2
	v_mov_b32_e32 v53, v2
	v_mov_b32_e32 v54, v2
	v_mov_b32_e32 v55, v2
	v_mov_b32_e32 v56, v2
	v_mov_b32_e32 v57, v2
	v_mov_b32_e32 v58, v2
	v_mov_b32_e32 v59, v2
	v_mov_b32_e32 v60, v2
	v_mov_b32_e32 v61, v2
	v_mov_b32_e32 v62, v2
	v_mov_b32_e32 v63, v2
	v_mov_b32_e32 v64, v2
	v_mov_b32_e32 v65, v2
	v_mov_b32_e32 v66, v2
	v_mov_b32_e32 v67, v2
	v_mov_b32_e32 v68, v2
	v_mov_b32_e32 v69, v2
	v_mov_b32_e32 v70, v2
	v_mov_b32_e32 v71, v2
	v_mov_b32_e32 v72, v2
	v_mov_b32_e32 v73, v2
	v_mov_b32_e32 v74, v2
	v_mov_b32_e32 v75, v2
	v_mov_b32_e32 v76, v2
	v_mov_b32_e32 v77, v2
	v_mov_b32_e32 v78, v2
	v_mov_b32_e32 v79, v2
	v_mov_b32_e32 v80, v2
	v_mov_b32_e32 v81, v2
	v_mov_b32_e32 v82, v2
	v_mov_b32_e32 v83, v2
	v_mov_b32_e32 v84, v2
	v_mov_b32_e32 v85, v2
	v_mov_b32_e32 v86, v2
	v_mov_b32_e32 v87, v2
	v_mov_b32_e32 v88, v2
	v_mov_b32_e32 v89, v2
	v_mov_b32_e32 v90, v2
	v_mov_b32_e32 v91, v2
	v_mov_b32_e32 v92, v2
	v_mov_b32_e32 v93, v2
	v_mov_b32_e32 v94, v2
	v_mov_b32_e32 v95, v2
	v_mov_b32_e32 v96, v2
	v_mov_b32_e32 v97, v2
	v_mov_b32_e32 v98, v2
	v_mov_b32_e32 v99, v2
	v_mov_b32_e32 v100, v2
	v_mov_b32_e32 v101, v2
	v_mov_b32_e32 v102, v2
	v_mov_b32_e32 v103, v2
	v_mov_b32_e32 v104, v2
	v_mov_b32_e32 v105, v2
	v_mov_b32_e32 v106, v2
	v_mov_b32_e32 v107, v2
	v_mov_b32_e32 v108, v2
	v_mov_b32_e32 v109, v2
	v_mov_b32_e32 v110, v2
	v_mov_b32_e32 v111, v2
	v_mov_b32_e32 v112, v2
	v_mov_b32_e32 v113, v2
	v_mov_b32_e32 v114, v2
	v_mov_b32_e32 v115, v2
	v_mov_b32_e32 v116, v2
	v_mov_b32_e32 v117, v2
	v_mov_b32_e32 v118, v2
	v_mov_b32_e32 v119, v2
	v_mov_b32_e32 v120, v2
	v_mov_b32_e32 v121, v2
	v_mov_b32_e32 v122, v2
	v_mov_b32_e32 v123, v2
	v_mov_b32_e32 v124, v2
	v_mov_b32_e32 v125, v2
	v_mov_b32_e32 v126, v2
	v_mov_b32_e32 v127, v2
	v_mov_b32_e32 v128, v2
	v_mov_b32_e32 v129, v2
	s_mov_b64 s[70:71], s[76:77]
	s_mov_b32 s87, s92
	s_andn2_b64 vcc, exec, s[78:79]
	s_mov_b64 s[46:47], s[72:73]
	s_cbranch_vccz .LBB0_209

; #define PG8_STAGE(bufoff, gbase, voff) do { _Pragma("unroll") for (int _i = 0; _i < 2; ++_i) \
;         __builtin_amdgcn_global_load_lds((const unsigned*)((const char*)(gbase) + (voff)[_i]), (PG8_LAS unsigned*)(lds + (bufoff) + ldsw + _i * 8192), 16, 0, 0); } while (0)
; #define PG8_LDA(dst, b, h) do { _Pragma("unroll") for (int m = 0; m < 4; ++m) _Pragma("unroll") for (int k = 0; k < 2; ++k) dst[m][k] = *(const PG8_LAS bf16x8*)(lds + PG8_SA(b, h) + aoff + m * 2048 + k * 1024); } while (0)
; #define PG8_LDB(dst, b, h) do { _Pragma("unroll") for (int n = 0; n < 2; ++n) _Pragma("unroll") for (int k = 0; k < 2; ++k) dst[n][k] = *(const PG8_LAS bf16x8*)(lds + PG8_SB(b, h) + boff + n * 2048 + k * 1024); } while (0)
; #define PG8_SCHED __builtin_amdgcn_sched_barrier(0)
; template <class Epi, class Sched, bool ALIGN_EPI = false, bool SP2 = false>
; __device__ __forceinline__ void gemm_phase(PG8_LAS unsigned char* lds, const Gemm g, const Sched& S, const Epi& E) {
;     ...
;         const bool has_next = S.next(ui + 1, nxt);
;         const char* nA = has_next ? (const char*)g.A + (size_t)nxt.pm * tstep : cA; const char* nB = has_next ? (const char*)g.Bt + (size_t)nxt.pn * tstep : cB;
;         for (int t = 0; t < nt; t += 2) {
;             const bool last = (t == nt - 2);
;             const char* a1 = cA + (size_t)(t + 1) * kstep;
;             const char* a2 = last ? nA : cA + (size_t)(t + 2) * kstep; const char* b2 = last ? nB : cB + (size_t)(t + 2) * kstep;
;             const char* a3 = a2 + kstep; const char* b3 = b2 + kstep;
;             if (last && has_next) S.a_ready(nxt);
;             if constexpr (SP2) {
;             PG8_LDB(B0, 0, 0); PG8_LDB(B1, 0, 1); PG8_SCHED; PG8_LDA(At, 0, 0); PG8_STAGE(PG8_SA(1, 1), a1 + hstep, voffA);
.LBB0_170:
	s_add_u32 s9, s70, s46
	s_addc_u32 s10, s71, s47
	s_add_u32 s9, s9, 0x100
	s_addc_u32 s10, s10, 0
	s_add_u32 s11, s93, s46
	s_addc_u32 s12, s94, s47
	s_add_i32 s13, 0, 0x10000
	s_cmpk_eq_i32 s46, 0xf00
	s_cselect_b32 s85, s4, s10
	s_cselect_b32 s84, s5, s9
	s_cselect_b32 s81, s6, s12
	s_cselect_b32 s80, s7, s11
	s_add_i32 s9, 0, 0x14000
	v_add_u32_e32 v160, s13, v139
	v_add_u32_e32 v178, s9, v139
	ds_read_b128 v[148:151], v160
	ds_read_b128 v[152:155], v160 offset:1024
	ds_read_b128 v[156:159], v160 offset:2048
	ds_read_b128 v[160:163], v160 offset:3072
	ds_read_b128 v[166:169], v178
	ds_read_b128 v[170:173], v178 offset:1024
	ds_read_b128 v[174:177], v178 offset:2048
	ds_read_b128 v[178:181], v178 offset:3072
	v_lshl_add_u64 v[194:195], v[144:145], 0, s[46:47]
	s_add_i32 m0, s1, 0xc000
	ds_read_b128 v[182:185], v165
	ds_read_b128 v[206:209], v165 offset:1024
	ds_read_b128 v[210:213], v165 offset:2048
	ds_read_b128 v[214:217], v165 offset:3072
	ds_read_b128 v[218:221], v165 offset:4096
	ds_read_b128 v[236:239], v165 offset:5120
	ds_read_b128 v[240:243], v165 offset:6144
	ds_read_b128 v[244:247], v165 offset:7168
	global_load_lds_dwordx4 v[194:195], off
	v_lshl_add_u64 v[194:195], v[146:147], 0, s[46:47]
	s_add_i32 m0, s1, 0xe000
	s_nop 0
	global_load_lds_dwordx4 v[194:195], off
	s_cmp_eq_u32 s101, 0
	s_cbranch_scc1 .Lwin_w0_std
	s_waitcnt vmcnt(24)
	s_branch .Lwin_w0_done

; #define PG8_STAGE(bufoff, gbase, voff) do { _Pragma("unroll") for (int _i = 0; _i < 2; ++_i) \
;         __builtin_amdgcn_global_load_lds((const unsigned*)((const char*)(gbase) + (voff)[_i]), (PG8_LAS unsigned*)(lds + (bufoff) + ldsw + _i * 8192), 16, 0, 0); } while (0)
; #define PG8_LDA(dst, b, h) do { _Pragma("unroll") for (int m = 0; m < 4; ++m) _Pragma("unroll") for (int k = 0; k < 2; ++k) dst[m][k] = *(const PG8_LAS bf16x8*)(lds + PG8_SA(b, h) + aoff + m * 2048 + k * 1024); } while (0)
; #define PG8_MMA(ai, bj, At, Bt) do { __builtin_amdgcn_s_setprio(1); _Pragma("unroll") for (int m = 0; m < 4; ++m) _Pragma("unroll") for (int n = 0; n < 2; ++n) _Pragma("unroll") for (int k = 0; k < 2; ++k) \
;         acc[ai][bj][m][n] = __builtin_amdgcn_mfma_f32_16x16x32_bf16(Bt[n][k], At[m][k], acc[ai][bj][m][n], 0, 0, 0); __builtin_amdgcn_s_setprio(0); } while (0)
; #define PG8_WAIT_V(n) asm volatile("s_waitcnt vmcnt(" #n ")" ::: "memory")
; #define PG8_WAIT_L(n) asm volatile("s_waitcnt lgkmcnt(" #n ")" ::: "memory")
; #define PG8_BAR __builtin_amdgcn_s_barrier()
; #define PG8_SCHED __builtin_amdgcn_sched_barrier(0)
; template <class Epi, class Sched, bool ALIGN_EPI = false, bool SP2 = false>
; __device__ __forceinline__ void gemm_phase(PG8_LAS unsigned char* lds, const Gemm g, const Sched& S, const Epi& E) {
;     ...
;             PG8_WAIT_V(8); PG8_WAIT_L(0); PG8_BAR; PG8_MMA(0, 0, At, B0); PG8_MMA(0, 1, At, B1); PG8_BAR; PG8_SCHED;
;             PG8_LDA(At, 0, 1); PG8_STAGE(PG8_SB(0, 0), b2, voffB); PG8_STAGE(PG8_SB(0, 1), b2 + hstepB, voffB); PG8_STAGE(PG8_SA(0, 0), a2, voffA);
.Lwin_w0_done:
	s_waitcnt lgkmcnt(0)
	s_barrier
	s_setprio 1
	s_waitcnt lgkmcnt(0)
	v_mfma_f32_16x16x32_bf16 v[126:129], v[148:151], v[182:185], v[126:129]
	v_mfma_f32_16x16x32_bf16 v[122:125], v[156:159], v[182:185], v[122:125]
	v_mfma_f32_16x16x32_bf16 v[118:121], v[148:151], v[210:213], v[118:121]
	v_mfma_f32_16x16x32_bf16 v[114:117], v[156:159], v[210:213], v[114:117]
	v_mfma_f32_16x16x32_bf16 v[110:113], v[148:151], v[218:221], v[110:113]
	v_mfma_f32_16x16x32_bf16 v[106:109], v[156:159], v[218:221], v[106:109]
	v_mfma_f32_16x16x32_bf16 v[102:105], v[148:151], v[240:243], v[102:105]
	v_mfma_f32_16x16x32_bf16 v[98:101], v[156:159], v[240:243], v[98:101]
	v_mfma_f32_16x16x32_bf16 v[126:129], v[152:155], v[206:209], v[126:129]
	v_mfma_f32_16x16x32_bf16 v[122:125], v[160:163], v[206:209], v[122:125]
	v_mfma_f32_16x16x32_bf16 v[118:121], v[152:155], v[214:217], v[118:121]
	v_mfma_f32_16x16x32_bf16 v[114:117], v[160:163], v[214:217], v[114:117]
	v_mfma_f32_16x16x32_bf16 v[110:113], v[152:155], v[236:239], v[110:113]
	v_mfma_f32_16x16x32_bf16 v[106:109], v[160:163], v[236:239], v[106:109]
	v_mfma_f32_16x16x32_bf16 v[102:105], v[152:155], v[244:247], v[102:105]
	v_mfma_f32_16x16x32_bf16 v[98:101], v[160:163], v[244:247], v[98:101]
	s_setprio 0
	s_setprio 1
	v_mfma_f32_16x16x32_bf16 v[94:97], v[166:169], v[182:185], v[94:97]
	v_mfma_f32_16x16x32_bf16 v[90:93], v[174:177], v[182:185], v[90:93]
	v_mfma_f32_16x16x32_bf16 v[86:89], v[166:169], v[210:213], v[86:89]
	v_mfma_f32_16x16x32_bf16 v[82:85], v[174:177], v[210:213], v[82:85]
	v_mfma_f32_16x16x32_bf16 v[78:81], v[166:169], v[218:221], v[78:81]
	v_mfma_f32_16x16x32_bf16 v[74:77], v[174:177], v[218:221], v[74:77]
	v_mfma_f32_16x16x32_bf16 v[70:73], v[166:169], v[240:243], v[70:73]
	v_mfma_f32_16x16x32_bf16 v[66:69], v[174:177], v[240:243], v[66:69]
	v_mfma_f32_16x16x32_bf16 v[94:97], v[170:173], v[206:209], v[94:97]
	v_mfma_f32_16x16x32_bf16 v[90:93], v[178:181], v[206:209], v[90:93]
	v_mfma_f32_16x16x32_bf16 v[86:89], v[170:173], v[214:217], v[86:89]
	v_mfma_f32_16x16x32_bf16 v[82:85], v[178:181], v[214:217], v[82:85]
	v_mfma_f32_16x16x32_bf16 v[78:81], v[170:173], v[236:239], v[78:81]
	v_mfma_f32_16x16x32_bf16 v[74:77], v[178:181], v[236:239], v[74:77]
	v_mfma_f32_16x16x32_bf16 v[70:73], v[170:173], v[244:247], v[70:73]
	v_mfma_f32_16x16x32_bf16 v[66:69], v[178:181], v[244:247], v[66:69]
	s_setprio 0
	s_barrier
	s_add_i32 s10, s13, s0
	v_lshl_add_u64 v[194:195], s[80:81], 0, v[132:133]
	s_mov_b32 m0, s10
	ds_read_b128 v[182:185], v165 offset:16384
	ds_read_b128 v[206:209], v165 offset:17408
	ds_read_b128 v[210:213], v165 offset:18432
	ds_read_b128 v[214:217], v165 offset:19456
	ds_read_b128 v[218:221], v165 offset:20480
	ds_read_b128 v[236:239], v165 offset:21504
	ds_read_b128 v[240:243], v165 offset:22528
	ds_read_b128 v[244:247], v165 offset:23552
	global_load_lds_dwordx4 v[194:195], off
	s_add_i32 m0, s10, 0x2000
	s_add_u32 s10, s80, 0x20000
	v_lshl_add_u64 v[196:197], s[80:81], 0, v[136:137]
	s_addc_u32 s11, s81, 0
	s_add_i32 s9, s9, s0
	global_load_lds_dwordx4 v[196:197], off
	v_lshl_add_u64 v[222:223], s[10:11], 0, v[132:133]
	s_mov_b32 m0, s9
	v_lshl_add_u64 v[234:235], s[84:85], 0, v[134:135]
	global_load_lds_dwordx4 v[222:223], off
	v_lshl_add_u64 v[222:223], s[10:11], 0, v[136:137]
	s_add_i32 m0, s9, 0x2000
	s_nop 0
	global_load_lds_dwordx4 v[222:223], off
	v_lshl_add_u64 v[222:223], s[84:85], 0, v[130:131]
	s_mov_b32 m0, s1
	s_nop 0
	global_load_lds_dwordx4 v[222:223], off
	s_mov_b32 m0, s25
	s_nop 0
	global_load_lds_dwordx4 v[234:235], off
	s_cmp_eq_u32 s101, 0
	s_cbranch_scc1 .Lwin_w1_std
	s_waitcnt vmcnt(24)
	s_mov_b32 s101, 0
	s_branch .Lwin_w1_done

; #define PG8_STAGE(bufoff, gbase, voff) do { _Pragma("unroll") for (int _i = 0; _i < 2; ++_i) \
;         __builtin_amdgcn_global_load_lds((const unsigned*)((const char*)(gbase) + (voff)[_i]), (PG8_LAS unsigned*)(lds + (bufoff) + ldsw + _i * 8192), 16, 0, 0); } while (0)
; #define PG8_LDA(dst, b, h) do { _Pragma("unroll") for (int m = 0; m < 4; ++m) _Pragma("unroll") for (int k = 0; k < 2; ++k) dst[m][k] = *(const PG8_LAS bf16x8*)(lds + PG8_SA(b, h) + aoff + m * 2048 + k * 1024); } while (0)
; #define PG8_LDB(dst, b, h) do { _Pragma("unroll") for (int n = 0; n < 2; ++n) _Pragma("unroll") for (int k = 0; k < 2; ++k) dst[n][k] = *(const PG8_LAS bf16x8*)(lds + PG8_SB(b, h) + boff + n * 2048 + k * 1024); } while (0)
; #define PG8_MMA(ai, bj, At, Bt) do { __builtin_amdgcn_s_setprio(1); _Pragma("unroll") for (int m = 0; m < 4; ++m) _Pragma("unroll") for (int n = 0; n < 2; ++n) _Pragma("unroll") for (int k = 0; k < 2; ++k) \
;         acc[ai][bj][m][n] = __builtin_amdgcn_mfma_f32_16x16x32_bf16(Bt[n][k], At[m][k], acc[ai][bj][m][n], 0, 0, 0); __builtin_amdgcn_s_setprio(0); } while (0)
; #define PG8_WAIT_V(n) asm volatile("s_waitcnt vmcnt(" #n ")" ::: "memory")
; #define PG8_WAIT_L(n) asm volatile("s_waitcnt lgkmcnt(" #n ")" ::: "memory")
; #define PG8_BAR __builtin_amdgcn_s_barrier()
; #define PG8_SCHED __builtin_amdgcn_sched_barrier(0)
; template <class Epi, class Sched, bool ALIGN_EPI = false, bool SP2 = false>
; __device__ __forceinline__ void gemm_phase(PG8_LAS unsigned char* lds, const Gemm g, const Sched& S, const Epi& E) {
;     ...
;             PG8_WAIT_V(8); PG8_WAIT_L(0); PG8_BAR; PG8_MMA(1, 0, At, B0); PG8_MMA(1, 1, At, B1); PG8_BAR; PG8_SCHED;
;             PG8_LDB(B0, 1, 0); PG8_LDB(B1, 1, 1); PG8_SCHED; PG8_LDA(At, 1, 0); PG8_STAGE(PG8_SA(0, 1), a2 + hstep, voffA);
;             PG8_WAIT_V(8); PG8_WAIT_L(0); PG8_BAR; PG8_MMA(0, 0, At, B0); PG8_MMA(0, 1, At, B1); PG8_BAR; PG8_SCHED;
.Lwin_w1_done:
	s_waitcnt lgkmcnt(0)
	s_barrier
	s_setprio 1
	s_waitcnt lgkmcnt(0)
	v_mfma_f32_16x16x32_bf16 v[62:65], v[148:151], v[182:185], v[62:65]
	v_mfma_f32_16x16x32_bf16 v[58:61], v[156:159], v[182:185], v[58:61]
	v_mfma_f32_16x16x32_bf16 v[54:57], v[148:151], v[210:213], v[54:57]
	v_mfma_f32_16x16x32_bf16 v[50:53], v[156:159], v[210:213], v[50:53]
	v_mfma_f32_16x16x32_bf16 v[46:49], v[148:151], v[218:221], v[46:49]
	v_mfma_f32_16x16x32_bf16 v[42:45], v[156:159], v[218:221], v[42:45]
	v_mfma_f32_16x16x32_bf16 v[38:41], v[148:151], v[240:243], v[38:41]
	v_mfma_f32_16x16x32_bf16 v[34:37], v[156:159], v[240:243], v[34:37]
	v_mfma_f32_16x16x32_bf16 v[62:65], v[152:155], v[206:209], v[62:65]
	v_mfma_f32_16x16x32_bf16 v[58:61], v[160:163], v[206:209], v[58:61]
	v_mfma_f32_16x16x32_bf16 v[54:57], v[152:155], v[214:217], v[54:57]
	v_mfma_f32_16x16x32_bf16 v[50:53], v[160:163], v[214:217], v[50:53]
	v_mfma_f32_16x16x32_bf16 v[46:49], v[152:155], v[236:239], v[46:49]
	v_mfma_f32_16x16x32_bf16 v[42:45], v[160:163], v[236:239], v[42:45]
	v_mfma_f32_16x16x32_bf16 v[38:41], v[152:155], v[244:247], v[38:41]
	v_mfma_f32_16x16x32_bf16 v[34:37], v[160:163], v[244:247], v[34:37]
	s_setprio 0
	s_setprio 1
	v_mfma_f32_16x16x32_bf16 v[30:33], v[166:169], v[182:185], v[30:33]
	v_mfma_f32_16x16x32_bf16 v[26:29], v[174:177], v[182:185], v[26:29]
	v_mfma_f32_16x16x32_bf16 v[22:25], v[166:169], v[210:213], v[22:25]
	v_mfma_f32_16x16x32_bf16 v[18:21], v[174:177], v[210:213], v[18:21]
	v_mfma_f32_16x16x32_bf16 v[14:17], v[166:169], v[218:221], v[14:17]
	v_mfma_f32_16x16x32_bf16 v[10:13], v[174:177], v[218:221], v[10:13]
	v_mfma_f32_16x16x32_bf16 v[6:9], v[166:169], v[240:243], v[6:9]
	v_mfma_f32_16x16x32_bf16 v[2:5], v[174:177], v[240:243], v[2:5]
	v_mfma_f32_16x16x32_bf16 v[30:33], v[170:173], v[206:209], v[30:33]
	v_mfma_f32_16x16x32_bf16 v[26:29], v[178:181], v[206:209], v[26:29]
	v_mfma_f32_16x16x32_bf16 v[22:25], v[170:173], v[214:217], v[22:25]
	v_mfma_f32_16x16x32_bf16 v[18:21], v[178:181], v[214:217], v[18:21]
	v_mfma_f32_16x16x32_bf16 v[14:17], v[170:173], v[236:239], v[14:17]
	v_mfma_f32_16x16x32_bf16 v[10:13], v[178:181], v[236:239], v[10:13]
	v_mfma_f32_16x16x32_bf16 v[6:9], v[170:173], v[244:247], v[6:9]
	v_mfma_f32_16x16x32_bf16 v[2:5], v[178:181], v[244:247], v[2:5]
	s_setprio 0
	s_barrier
	s_add_i32 s9, 0, 0x18000
	s_add_i32 s12, 0, 0x1c000
	v_add_u32_e32 v160, s9, v139
	v_add_u32_e32 v178, s12, v139
	ds_read_b128 v[148:151], v160
	ds_read_b128 v[152:155], v160 offset:1024
	ds_read_b128 v[156:159], v160 offset:2048
	ds_read_b128 v[160:163], v160 offset:3072
	ds_read_b128 v[166:169], v178
	ds_read_b128 v[170:173], v178 offset:1024
	ds_read_b128 v[174:177], v178 offset:2048
	ds_read_b128 v[178:181], v178 offset:3072
	s_add_u32 s10, s84, 0x80000
	s_addc_u32 s11, s85, 0
	s_mov_b32 m0, s42
	v_lshl_add_u64 v[198:199], s[10:11], 0, v[130:131]
	ds_read_b128 v[182:185], v165 offset:32768
	ds_read_b128 v[206:209], v165 offset:33792
	ds_read_b128 v[210:213], v165 offset:34816
	ds_read_b128 v[214:217], v165 offset:35840
	ds_read_b128 v[218:221], v165 offset:36864
	ds_read_b128 v[236:239], v165 offset:37888
	ds_read_b128 v[240:243], v165 offset:38912
	ds_read_b128 v[244:247], v165 offset:39936
	global_load_lds_dwordx4 v[198:199], off
	v_lshl_add_u64 v[198:199], s[10:11], 0, v[134:135]
	s_mov_b32 m0, s51
	s_nop 0
	global_load_lds_dwordx4 v[198:199], off
	s_waitcnt vmcnt(8)
	s_waitcnt lgkmcnt(0)
	s_barrier
	s_setprio 1
	s_waitcnt lgkmcnt(0)
	v_mfma_f32_16x16x32_bf16 v[126:129], v[148:151], v[182:185], v[126:129]
	v_mfma_f32_16x16x32_bf16 v[122:125], v[156:159], v[182:185], v[122:125]
	v_mfma_f32_16x16x32_bf16 v[118:121], v[148:151], v[210:213], v[118:121]
	v_mfma_f32_16x16x32_bf16 v[114:117], v[156:159], v[210:213], v[114:117]
	v_mfma_f32_16x16x32_bf16 v[110:113], v[148:151], v[218:221], v[110:113]
	v_mfma_f32_16x16x32_bf16 v[106:109], v[156:159], v[218:221], v[106:109]
	v_mfma_f32_16x16x32_bf16 v[102:105], v[148:151], v[240:243], v[102:105]
	v_mfma_f32_16x16x32_bf16 v[98:101], v[156:159], v[240:243], v[98:101]
	v_mfma_f32_16x16x32_bf16 v[126:129], v[152:155], v[206:209], v[126:129]
	v_mfma_f32_16x16x32_bf16 v[122:125], v[160:163], v[206:209], v[122:125]
	v_mfma_f32_16x16x32_bf16 v[118:121], v[152:155], v[214:217], v[118:121]
	v_mfma_f32_16x16x32_bf16 v[114:117], v[160:163], v[214:217], v[114:117]
	v_mfma_f32_16x16x32_bf16 v[110:113], v[152:155], v[236:239], v[110:113]
	v_mfma_f32_16x16x32_bf16 v[106:109], v[160:163], v[236:239], v[106:109]
	v_mfma_f32_16x16x32_bf16 v[102:105], v[152:155], v[244:247], v[102:105]
	v_mfma_f32_16x16x32_bf16 v[98:101], v[160:163], v[244:247], v[98:101]
	s_setprio 0
	s_setprio 1
	v_mfma_f32_16x16x32_bf16 v[94:97], v[166:169], v[182:185], v[94:97]
	v_mfma_f32_16x16x32_bf16 v[90:93], v[174:177], v[182:185], v[90:93]
	v_mfma_f32_16x16x32_bf16 v[86:89], v[166:169], v[210:213], v[86:89]
	v_mfma_f32_16x16x32_bf16 v[82:85], v[174:177], v[210:213], v[82:85]
	v_mfma_f32_16x16x32_bf16 v[78:81], v[166:169], v[218:221], v[78:81]
	v_mfma_f32_16x16x32_bf16 v[74:77], v[174:177], v[218:221], v[74:77]
	v_mfma_f32_16x16x32_bf16 v[70:73], v[166:169], v[240:243], v[70:73]
	v_mfma_f32_16x16x32_bf16 v[66:69], v[174:177], v[240:243], v[66:69]
	v_mfma_f32_16x16x32_bf16 v[94:97], v[170:173], v[206:209], v[94:97]
	v_mfma_f32_16x16x32_bf16 v[90:93], v[178:181], v[206:209], v[90:93]
	v_mfma_f32_16x16x32_bf16 v[86:89], v[170:173], v[214:217], v[86:89]
	v_mfma_f32_16x16x32_bf16 v[82:85], v[178:181], v[214:217], v[82:85]
	v_mfma_f32_16x16x32_bf16 v[78:81], v[170:173], v[236:239], v[78:81]
	v_mfma_f32_16x16x32_bf16 v[74:77], v[178:181], v[236:239], v[74:77]
	v_mfma_f32_16x16x32_bf16 v[70:73], v[170:173], v[244:247], v[70:73]
	v_mfma_f32_16x16x32_bf16 v[66:69], v[178:181], v[244:247], v[66:69]
	s_setprio 0
	s_barrier
; #define PG8_STAGE(bufoff, gbase, voff) do { _Pragma("unroll") for (int _i = 0; _i < 2; ++_i) \
;         __builtin_amdgcn_global_load_lds((const unsigned*)((const char*)(gbase) + (voff)[_i]), (PG8_LAS unsigned*)(lds + (bufoff) + ldsw + _i * 8192), 16, 0, 0); } while (0)
; #define PG8_LDA(dst, b, h) do { _Pragma("unroll") for (int m = 0; m < 4; ++m) _Pragma("unroll") for (int k = 0; k < 2; ++k) dst[m][k] = *(const PG8_LAS bf16x8*)(lds + PG8_SA(b, h) + aoff + m * 2048 + k * 1024); } while (0)
; #define PG8_MMA(ai, bj, At, Bt) do { __builtin_amdgcn_s_setprio(1); _Pragma("unroll") for (int m = 0; m < 4; ++m) _Pragma("unroll") for (int n = 0; n < 2; ++n) _Pragma("unroll") for (int k = 0; k < 2; ++k) \
;         acc[ai][bj][m][n] = __builtin_amdgcn_mfma_f32_16x16x32_bf16(Bt[n][k], At[m][k], acc[ai][bj][m][n], 0, 0, 0); __builtin_amdgcn_s_setprio(0); } while (0)
; #define PG8_WAIT_V(n) asm volatile("s_waitcnt vmcnt(" #n ")" ::: "memory")
; #define PG8_WAIT_L(n) asm volatile("s_waitcnt lgkmcnt(" #n ")" ::: "memory")
; #define PG8_BAR __builtin_amdgcn_s_barrier()
; #define PG8_SCHED __builtin_amdgcn_sched_barrier(0)
; template <class Epi, class Sched, bool ALIGN_EPI = false, bool SP2 = false>
; __device__ __forceinline__ void gemm_phase(PG8_LAS unsigned char* lds, const Gemm g, const Sched& S, const Epi& E) {
;     ...
;             PG8_LDA(At, 1, 1); PG8_STAGE(PG8_SB(1, 0), b3, voffB); PG8_STAGE(PG8_SB(1, 1), b3 + hstepB, voffB); PG8_STAGE(PG8_SA(1, 0), a3, voffA);
;             PG8_WAIT_V(8); PG8_WAIT_L(0); PG8_BAR; PG8_MMA(1, 0, At, B0); PG8_MMA(1, 1, At, B1); PG8_BAR; PG8_SCHED;
;     ...
;         if constexpr (ALIGN_EPI) { if (wr == 0) PG8_BAR; }
	s_add_i32 s9, s9, s0
	v_lshl_add_u64 v[194:195], v[194:195], 0, s[60:61]
	s_mov_b32 m0, s9
	ds_read_b128 v[182:185], v165 offset:49152
	ds_read_b128 v[206:209], v165 offset:50176
	ds_read_b128 v[210:213], v165 offset:51200
	ds_read_b128 v[214:217], v165 offset:52224
	ds_read_b128 v[218:221], v165 offset:53248
	ds_read_b128 v[236:239], v165 offset:54272
	ds_read_b128 v[240:243], v165 offset:55296
	ds_read_b128 v[244:247], v165 offset:56320
	global_load_lds_dwordx4 v[194:195], off
	s_add_i32 m0, s9, 0x2000
	s_add_u32 s10, s80, 0x20080
	v_lshl_add_u64 v[194:195], v[196:197], 0, s[60:61]
	s_addc_u32 s11, s81, 0
	s_add_i32 s9, s12, s0
	global_load_lds_dwordx4 v[194:195], off
	v_lshl_add_u64 v[194:195], s[10:11], 0, v[132:133]
	s_mov_b32 m0, s9
	s_nop 0
	global_load_lds_dwordx4 v[194:195], off
	v_lshl_add_u64 v[194:195], s[10:11], 0, v[136:137]
	s_add_i32 m0, s9, 0x2000
	s_nop 0
	global_load_lds_dwordx4 v[194:195], off
	v_lshl_add_u64 v[194:195], v[222:223], 0, s[60:61]
	s_mov_b32 m0, s66
	s_nop 0
	global_load_lds_dwordx4 v[194:195], off
	v_lshl_add_u64 v[194:195], v[234:235], 0, s[60:61]
	s_mov_b32 m0, s67
	s_nop 0
	global_load_lds_dwordx4 v[194:195], off
	s_waitcnt vmcnt(8)
	s_waitcnt lgkmcnt(0)
	s_barrier
	s_setprio 1
	s_waitcnt lgkmcnt(0)
	v_mfma_f32_16x16x32_bf16 v[62:65], v[148:151], v[182:185], v[62:65]
	v_mfma_f32_16x16x32_bf16 v[58:61], v[156:159], v[182:185], v[58:61]
	v_mfma_f32_16x16x32_bf16 v[54:57], v[148:151], v[210:213], v[54:57]
	v_mfma_f32_16x16x32_bf16 v[50:53], v[156:159], v[210:213], v[50:53]
	v_mfma_f32_16x16x32_bf16 v[46:49], v[148:151], v[218:221], v[46:49]
	v_mfma_f32_16x16x32_bf16 v[42:45], v[156:159], v[218:221], v[42:45]
	v_mfma_f32_16x16x32_bf16 v[38:41], v[148:151], v[240:243], v[38:41]
	v_mfma_f32_16x16x32_bf16 v[34:37], v[156:159], v[240:243], v[34:37]
	v_mfma_f32_16x16x32_bf16 v[62:65], v[152:155], v[206:209], v[62:65]
	v_mfma_f32_16x16x32_bf16 v[58:61], v[160:163], v[206:209], v[58:61]
	v_mfma_f32_16x16x32_bf16 v[54:57], v[152:155], v[214:217], v[54:57]
	v_mfma_f32_16x16x32_bf16 v[50:53], v[160:163], v[214:217], v[50:53]
	v_mfma_f32_16x16x32_bf16 v[46:49], v[152:155], v[236:239], v[46:49]
	v_mfma_f32_16x16x32_bf16 v[42:45], v[160:163], v[236:239], v[42:45]
	v_mfma_f32_16x16x32_bf16 v[38:41], v[152:155], v[244:247], v[38:41]
	v_mfma_f32_16x16x32_bf16 v[34:37], v[160:163], v[244:247], v[34:37]
	s_setprio 0
	s_setprio 1
	v_mfma_f32_16x16x32_bf16 v[30:33], v[166:169], v[182:185], v[30:33]
	v_mfma_f32_16x16x32_bf16 v[26:29], v[174:177], v[182:185], v[26:29]
	v_mfma_f32_16x16x32_bf16 v[22:25], v[166:169], v[210:213], v[22:25]
	v_mfma_f32_16x16x32_bf16 v[18:21], v[174:177], v[210:213], v[18:21]
	v_mfma_f32_16x16x32_bf16 v[14:17], v[166:169], v[218:221], v[14:17]
	v_mfma_f32_16x16x32_bf16 v[10:13], v[174:177], v[218:221], v[10:13]
	v_mfma_f32_16x16x32_bf16 v[6:9], v[166:169], v[240:243], v[6:9]
	v_mfma_f32_16x16x32_bf16 v[2:5], v[174:177], v[240:243], v[2:5]
	v_mfma_f32_16x16x32_bf16 v[30:33], v[170:173], v[206:209], v[30:33]
	v_mfma_f32_16x16x32_bf16 v[26:29], v[178:181], v[206:209], v[26:29]
	v_mfma_f32_16x16x32_bf16 v[22:25], v[170:173], v[214:217], v[22:25]
	v_mfma_f32_16x16x32_bf16 v[18:21], v[178:181], v[214:217], v[18:21]
	v_mfma_f32_16x16x32_bf16 v[14:17], v[170:173], v[236:239], v[14:17]
	v_mfma_f32_16x16x32_bf16 v[10:13], v[178:181], v[236:239], v[10:13]
	v_mfma_f32_16x16x32_bf16 v[6:9], v[170:173], v[244:247], v[6:9]
	v_mfma_f32_16x16x32_bf16 v[2:5], v[178:181], v[244:247], v[2:5]
	s_setprio 0
	s_barrier
	s_add_i32 s8, s8, 2
	s_add_u32 s46, s46, 0x100
	s_addc_u32 s47, s47, 0
	s_cmp_gt_u32 s8, 29
	s_cbranch_scc0 .LBB0_170
	s_and_b64 vcc, exec, s[54:55]
	s_cbranch_vccz .LBB0_173
	s_barrier

; #define PG8_STAGE(bufoff, gbase, voff) do { _Pragma("unroll") for (int _i = 0; _i < 2; ++_i) \
;         __builtin_amdgcn_global_load_lds((const unsigned*)((const char*)(gbase) + (voff)[_i]), (PG8_LAS unsigned*)(lds + (bufoff) + ldsw + _i * 8192), 16, 0, 0); } while (0)
; #define PG8_WAIT_V(n) asm volatile("s_waitcnt vmcnt(" #n ")" ::: "memory")
; #define PG8_BAR __builtin_amdgcn_s_barrier()
; template <class Epi, class Sched, bool ALIGN_EPI = false, bool SP2 = false>
; __device__ __forceinline__ void gemm_phase(PG8_LAS unsigned char* lds, const Gemm g, const Sched& S, const Epi& E) {
;     ...
;     f32x4 acc[2][2][4][2];
; #pragma unroll
;     for (int a = 0; a < 2; ++a)
; #pragma unroll
;         for (int b = 0; b < 2; ++b)
; #pragma unroll
;             for (int m = 0; m < 4; ++m)
; #pragma unroll
;                 for (int n = 0; n < 2; ++n) acc[a][b][m][n] = (f32x4){0.f, 0.f, 0.f, 0.f};
;     bf16x8 At[4][2], B0[2][2], B1[2][2];
;     const char* cA = (const char*)g.A + (size_t)cur.pm * tstep; const char* cB = (const char*)g.Bt + (size_t)cur.pn * tstep;
;     S.a_ready(cur);
;     if constexpr (SP2) {
;         PG8_STAGE(PG8_SB(0, 0), cB, voffB); PG8_STAGE(PG8_SB(0, 1), cB + hstepB, voffB); PG8_STAGE(PG8_SA(0, 0), cA, voffA); PG8_STAGE(PG8_SA(0, 1), cA + hstep, voffA);
;         if (wr == 1) PG8_BAR;
;         PG8_WAIT_V(2); PG8_BAR;
;         PG8_STAGE(PG8_SB(1, 0), cB + kstep, voffB); PG8_STAGE(PG8_SA(1, 0), cA + kstep, voffA); PG8_STAGE(PG8_SB(1, 1), cB + hstepB + kstep, voffB);
;         PG8_WAIT_V(6); PG8_BAR;
;     } else {
;         PG8_STAGE(PG8_SB(0, 0), cB, voffB); PG8_STAGE(PG8_SA(0, 0), cA, voffA); PG8_STAGE(PG8_SB(0, 1), cB + hstepB, voffB); PG8_STAGE(PG8_SA(0, 1), cA + hstep, voffA);
;         if (wr == 1) PG8_BAR;
;         PG8_WAIT_V(4); PG8_BAR;
;         PG8_STAGE(PG8_SB(1, 0), cB + kstep, voffB); PG8_STAGE(PG8_SA(1, 0), cA + kstep, voffA); PG8_STAGE(PG8_SB(1, 1), cB + hstepB + kstep, voffB);
;         PG8_WAIT_V(6); PG8_BAR;
;     }
.LBB0_1224:
	v_lshrrev_b32_e32 v17, 1, v26
	v_readlane_b32 s80, v252, 17
	s_lshl_b32 s6, s59, 27
	v_and_b32_e32 v17, 24, v17
	v_mov_b32_e32 v131, v191
	v_readlane_b32 s81, v252, 18
	s_and_b32 s6, s6, 0x8000000
	v_and_b32_e32 v16, 15, v26
	v_lshlrev_b32_e32 v18, 1, v17
	v_lshl_add_u64 v[12:13], s[80:81], 0, v[130:131]
	v_mov_b32_e32 v135, v191
	s_add_u32 s54, s64, s6
	v_lshl_or_b32 v1, s5, 6, v16
	v_lshl_or_b32 v18, v16, 6, v18
	v_lshlrev_b32_e32 v16, 2, v16
	v_lshl_add_u64 v[14:15], s[80:81], 0, v[134:135]
	s_addc_u32 s55, s65, 0
	s_and_b32 s4, s4, 3
	s_lshl_b32 s6, s5, 13
	v_and_b32_e32 v19, 32, v16
	s_add_i32 m0, s51, 0x18000
	v_lshl_add_u64 v[12:13], v[12:13], 0, s[60:61]
	v_bitop3_b32 v20, v18, s6, v19 bitop3:0xde
	s_lshl_b32 s6, s4, 12
	s_waitcnt vmcnt(2)
	s_barrier
	global_load_lds_dwordx4 v[12:13], off
	v_lshl_add_u64 v[12:13], v[14:15], 0, s[60:61]
	s_add_i32 m0, s51, 0x1a000
	s_add_i32 s82, s51, 0x8000
	v_bitop3_b32 v145, v18, s6, v19 bitop3:0xde
	global_load_lds_dwordx4 v[12:13], off
	v_lshl_add_u64 v[2:3], v[2:3], 0, s[60:61]
	s_mov_b32 m0, s82
	s_add_i32 s86, s51, 0xa000
	v_readlane_b32 s6, v249, 15
	global_load_lds_dwordx4 v[2:3], off
	v_lshl_add_u64 v[2:3], v[4:5], 0, s[60:61]
	s_mov_b32 m0, s86
	v_readlane_b32 s7, v249, 16
	global_load_lds_dwordx4 v[2:3], off
	s_add_i32 m0, s51, 0x1c000
	v_lshl_add_u64 v[2:3], s[6:7], 0, v[130:131]
	global_load_lds_dwordx4 v[2:3], off
	v_lshl_add_u64 v[2:3], s[6:7], 0, v[134:135]
	s_add_i32 m0, s51, 0x1e000
	s_cmpk_lt_u32 s36, 0x100
	global_load_lds_dwordx4 v[2:3], off
	v_lshlrev_b32_e32 v2, 15, v6
	v_and_b32_e32 v2, 0xffff0000, v2
	v_lshl_add_u32 v2, v7, 12, v2
	v_and_b32_e32 v3, 1, v6
	v_lshl_or_b32 v2, v3, 6, v2
	v_lshl_add_u32 v136, v8, 1, v2
	v_lshlrev_b32_e32 v2, 15, v9
	s_cselect_b64 s[62:63], -1, 0
	s_lshl_b32 s5, s5, 8
	v_and_b32_e32 v2, 0xffff0000, v2
	s_add_i32 s5, s5, 0
	v_lshl_add_u32 v2, v10, 12, v2
	v_and_b32_e32 v3, 1, v9
	s_waitcnt vmcnt(6)
	s_add_i32 s5, s5, 0x20000
	v_lshl_or_b32 v2, v3, 6, v2
	v_add_u32_e32 v147, s5, v16
	v_lshl_or_b32 v149, s4, 6, v17
	v_lshl_add_u32 v138, v11, 1, v2
	v_mov_b32_e32 v2, 0
	v_readlane_b32 s4, v249, 28
	v_mov_b32_e32 v137, v191
	v_mov_b32_e32 v139, v191
	s_mov_b32 s95, 0
	v_add_u32_e32 v151, 0, v20
	v_readlane_b32 s87, v249, 30
	s_mov_b32 s94, s4
	v_mov_b32_e32 v3, v2
	v_mov_b32_e32 v4, v2
	v_mov_b32_e32 v5, v2
	v_mov_b32_e32 v6, v2
	v_mov_b32_e32 v7, v2
	v_mov_b32_e32 v8, v2
	v_mov_b32_e32 v9, v2
	v_mov_b32_e32 v10, v2
	v_mov_b32_e32 v11, v2
	v_mov_b32_e32 v12, v2
	v_mov_b32_e32 v13, v2
	v_mov_b32_e32 v14, v2
	v_mov_b32_e32 v15, v2
	v_mov_b32_e32 v16, v2
	v_mov_b32_e32 v17, v2
	v_mov_b32_e32 v18, v2
	v_mov_b32_e32 v19, v2
	v_mov_b32_e32 v20, v2
	v_mov_b32_e32 v21, v2
	v_mov_b32_e32 v22, v2
	v_mov_b32_e32 v23, v2
	v_mov_b32_e32 v24, v2
	v_mov_b32_e32 v25, v2
	v_mov_b32_e32 v26, v2
	v_mov_b32_e32 v27, v2
	v_mov_b32_e32 v28, v2
	v_mov_b32_e32 v29, v2
	v_mov_b32_e32 v30, v2
	v_mov_b32_e32 v31, v2
	v_mov_b32_e32 v32, v2
	v_mov_b32_e32 v33, v2
	v_mov_b32_e32 v34, v2
	v_mov_b32_e32 v35, v2
	v_mov_b32_e32 v36, v2
	v_mov_b32_e32 v37, v2
	v_mov_b32_e32 v38, v2
	v_mov_b32_e32 v39, v2
	v_mov_b32_e32 v40, v2
	v_mov_b32_e32 v41, v2
	v_mov_b32_e32 v42, v2
	v_mov_b32_e32 v43, v2
	v_mov_b32_e32 v44, v2
	v_mov_b32_e32 v45, v2
	v_mov_b32_e32 v46, v2
	v_mov_b32_e32 v47, v2
	v_mov_b32_e32 v48, v2
	v_mov_b32_e32 v49, v2
	v_mov_b32_e32 v50, v2
	v_mov_b32_e32 v51, v2
	v_mov_b32_e32 v52, v2
	v_mov_b32_e32 v53, v2
	v_mov_b32_e32 v54, v2
	v_mov_b32_e32 v55, v2
	v_mov_b32_e32 v56, v2
	v_mov_b32_e32 v57, v2
	v_mov_b32_e32 v58, v2
	v_mov_b32_e32 v59, v2
	v_mov_b32_e32 v60, v2
	v_mov_b32_e32 v61, v2
	v_mov_b32_e32 v62, v2
	v_mov_b32_e32 v63, v2
	v_mov_b32_e32 v64, v2
	v_mov_b32_e32 v65, v2
	v_mov_b32_e32 v66, v2
	v_mov_b32_e32 v67, v2
	v_mov_b32_e32 v68, v2
	v_mov_b32_e32 v69, v2
	v_mov_b32_e32 v70, v2
	v_mov_b32_e32 v71, v2
	v_mov_b32_e32 v72, v2
	v_mov_b32_e32 v73, v2
	v_mov_b32_e32 v74, v2
	v_mov_b32_e32 v75, v2
	v_mov_b32_e32 v76, v2
	v_mov_b32_e32 v77, v2
	v_mov_b32_e32 v78, v2
	v_mov_b32_e32 v79, v2
	v_mov_b32_e32 v80, v2
	v_mov_b32_e32 v81, v2
	v_mov_b32_e32 v82, v2
	v_mov_b32_e32 v83, v2
	v_mov_b32_e32 v84, v2
	v_mov_b32_e32 v85, v2
	v_mov_b32_e32 v86, v2
	v_mov_b32_e32 v87, v2
	v_mov_b32_e32 v88, v2
	v_mov_b32_e32 v89, v2
	v_mov_b32_e32 v90, v2
	v_mov_b32_e32 v91, v2
	v_mov_b32_e32 v92, v2
	v_mov_b32_e32 v93, v2
	v_mov_b32_e32 v94, v2
	v_mov_b32_e32 v95, v2
	v_mov_b32_e32 v96, v2
	v_mov_b32_e32 v97, v2
	v_mov_b32_e32 v98, v2
	v_mov_b32_e32 v99, v2
	v_mov_b32_e32 v100, v2
	v_mov_b32_e32 v101, v2
	v_mov_b32_e32 v102, v2
	v_mov_b32_e32 v103, v2
	v_mov_b32_e32 v104, v2
	v_mov_b32_e32 v105, v2
	v_mov_b32_e32 v106, v2
	v_mov_b32_e32 v107, v2
	v_mov_b32_e32 v108, v2
	v_mov_b32_e32 v109, v2
	v_mov_b32_e32 v110, v2
	v_mov_b32_e32 v111, v2
	v_mov_b32_e32 v112, v2
	v_mov_b32_e32 v113, v2
	v_mov_b32_e32 v114, v2
	v_mov_b32_e32 v115, v2
	v_mov_b32_e32 v116, v2
	v_mov_b32_e32 v117, v2
	v_mov_b32_e32 v118, v2
	v_mov_b32_e32 v119, v2
	v_mov_b32_e32 v120, v2
	v_mov_b32_e32 v121, v2
	v_mov_b32_e32 v122, v2
	v_mov_b32_e32 v123, v2
	v_mov_b32_e32 v124, v2
	v_mov_b32_e32 v125, v2
	v_mov_b32_e32 v126, v2
	v_mov_b32_e32 v127, v2
	v_mov_b32_e32 v128, v2
	v_mov_b32_e32 v129, v2
	s_barrier
	v_readlane_b32 s5, v249, 29
	s_mov_b32 s101, 0
	s_branch .LBB0_1226
; #define PG8_BAR __builtin_amdgcn_s_barrier()
; template <class Epi, class Sched, bool ALIGN_EPI = false, bool SP2 = false>
; __device__ __forceinline__ void gemm_phase(PG8_LAS unsigned char* lds, const Gemm g, const Sched& S, const Epi& E) {
;     ...
; #pragma unroll
;         for (int a = 0; a < 2; ++a)
; #pragma unroll
;             for (int b = 0; b < 2; ++b)
; #pragma unroll
;                 for (int m = 0; m < 4; ++m)
; #pragma unroll
;                     for (int n = 0; n < 2; ++n) acc[a][b][m][n] = (f32x4){0.f, 0.f, 0.f, 0.f};
;         cur = nxt; cA = nA; cB = nB; ++ui;
;         if constexpr (ALIGN_EPI) { if (wr == 1) PG8_BAR; }
.LBB0_1225:
	s_mov_b32 s101, 1
	v_mov_b32_e32 v2, 0
	s_mov_b32 s87, s70
	s_mov_b32 s94, s72
	v_mov_b32_e32 v3, v2
	v_mov_b32_e32 v4, v2
	v_mov_b32_e32 v5, v2
	v_mov_b32_e32 v6, v2
	v_mov_b32_e32 v7, v2
	v_mov_b32_e32 v8, v2
	v_mov_b32_e32 v9, v2
	v_mov_b32_e32 v10, v2
	v_mov_b32_e32 v11, v2
	v_mov_b32_e32 v12, v2
	v_mov_b32_e32 v13, v2
	v_mov_b32_e32 v14, v2
	v_mov_b32_e32 v15, v2
	v_mov_b32_e32 v16, v2
	v_mov_b32_e32 v17, v2
	v_mov_b32_e32 v18, v2
	v_mov_b32_e32 v19, v2
	v_mov_b32_e32 v20, v2
	v_mov_b32_e32 v21, v2
	v_mov_b32_e32 v22, v2
	v_mov_b32_e32 v23, v2
	v_mov_b32_e32 v24, v2
	v_mov_b32_e32 v25, v2
	v_mov_b32_e32 v26, v2
	v_mov_b32_e32 v27, v2
	v_mov_b32_e32 v28, v2
	v_mov_b32_e32 v29, v2
	v_mov_b32_e32 v30, v2
	v_mov_b32_e32 v31, v2
	v_mov_b32_e32 v32, v2
	v_mov_b32_e32 v33, v2
	v_mov_b32_e32 v34, v2
	v_mov_b32_e32 v35, v2
	v_mov_b32_e32 v36, v2
	v_mov_b32_e32 v37, v2
	v_mov_b32_e32 v38, v2
	v_mov_b32_e32 v39, v2
	v_mov_b32_e32 v40, v2
	v_mov_b32_e32 v41, v2
	v_mov_b32_e32 v42, v2
	v_mov_b32_e32 v43, v2
	v_mov_b32_e32 v44, v2
	v_mov_b32_e32 v45, v2
	v_mov_b32_e32 v46, v2
	v_mov_b32_e32 v47, v2
	v_mov_b32_e32 v48, v2
	v_mov_b32_e32 v49, v2
	v_mov_b32_e32 v50, v2
	v_mov_b32_e32 v51, v2
	v_mov_b32_e32 v52, v2
	v_mov_b32_e32 v53, v2
	v_mov_b32_e32 v54, v2
	v_mov_b32_e32 v55, v2
	v_mov_b32_e32 v56, v2
	v_mov_b32_e32 v57, v2
	v_mov_b32_e32 v58, v2
	v_mov_b32_e32 v59, v2
	v_mov_b32_e32 v60, v2
	v_mov_b32_e32 v61, v2
	v_mov_b32_e32 v62, v2
	v_mov_b32_e32 v63, v2
	v_mov_b32_e32 v64, v2
	v_mov_b32_e32 v65, v2
	v_mov_b32_e32 v66, v2
	v_mov_b32_e32 v67, v2
	v_mov_b32_e32 v68, v2
	v_mov_b32_e32 v69, v2
	v_mov_b32_e32 v70, v2
	v_mov_b32_e32 v71, v2
	v_mov_b32_e32 v72, v2
	v_mov_b32_e32 v73, v2
	v_mov_b32_e32 v74, v2
	v_mov_b32_e32 v75, v2
	v_mov_b32_e32 v76, v2
	v_mov_b32_e32 v77, v2
	v_mov_b32_e32 v78, v2
	v_mov_b32_e32 v79, v2
	v_mov_b32_e32 v80, v2
	v_mov_b32_e32 v81, v2
	v_mov_b32_e32 v82, v2
	v_mov_b32_e32 v83, v2
	v_mov_b32_e32 v84, v2
	v_mov_b32_e32 v85, v2
	v_mov_b32_e32 v86, v2
	v_mov_b32_e32 v87, v2
	v_mov_b32_e32 v88, v2
	v_mov_b32_e32 v89, v2
	v_mov_b32_e32 v90, v2
	v_mov_b32_e32 v91, v2
	v_mov_b32_e32 v92, v2
	v_mov_b32_e32 v93, v2
	v_mov_b32_e32 v94, v2
	v_mov_b32_e32 v95, v2
	v_mov_b32_e32 v96, v2
	v_mov_b32_e32 v97, v2
	v_mov_b32_e32 v98, v2
	v_mov_b32_e32 v99, v2
	v_mov_b32_e32 v100, v2
	v_mov_b32_e32 v101, v2
	v_mov_b32_e32 v102, v2
	v_mov_b32_e32 v103, v2
	v_mov_b32_e32 v104, v2
	v_mov_b32_e32 v105, v2
	v_mov_b32_e32 v106, v2
	v_mov_b32_e32 v107, v2
	v_mov_b32_e32 v108, v2
	v_mov_b32_e32 v109, v2
	v_mov_b32_e32 v110, v2
	v_mov_b32_e32 v111, v2
	v_mov_b32_e32 v112, v2
	v_mov_b32_e32 v113, v2
	v_mov_b32_e32 v114, v2
	v_mov_b32_e32 v115, v2
	v_mov_b32_e32 v116, v2
	v_mov_b32_e32 v117, v2
	v_mov_b32_e32 v118, v2
	v_mov_b32_e32 v119, v2
	v_mov_b32_e32 v120, v2
	v_mov_b32_e32 v121, v2
	v_mov_b32_e32 v122, v2
	v_mov_b32_e32 v123, v2
	v_mov_b32_e32 v124, v2
	v_mov_b32_e32 v125, v2
	v_mov_b32_e32 v126, v2
	v_mov_b32_e32 v127, v2
	v_mov_b32_e32 v128, v2
	v_mov_b32_e32 v129, v2
	s_mov_b64 s[68:69], s[78:79]
	s_mov_b32 s95, s96
	s_andn2_b64 vcc, exec, s[38:39]
	s_mov_b64 s[80:81], s[76:77]
	s_cbranch_vccz .LBB0_1240

; #define PG8_STAGE(bufoff, gbase, voff) do { _Pragma("unroll") for (int _i = 0; _i < 2; ++_i) \
;         __builtin_amdgcn_global_load_lds((const unsigned*)((const char*)(gbase) + (voff)[_i]), (PG8_LAS unsigned*)(lds + (bufoff) + ldsw + _i * 8192), 16, 0, 0); } while (0)
; #define PG8_LDA(dst, b, h) do { _Pragma("unroll") for (int m = 0; m < 4; ++m) _Pragma("unroll") for (int k = 0; k < 2; ++k) dst[m][k] = *(const PG8_LAS bf16x8*)(lds + PG8_SA(b, h) + aoff + m * 2048 + k * 1024); } while (0)
; #define PG8_LDB(dst, b, h) do { _Pragma("unroll") for (int n = 0; n < 2; ++n) _Pragma("unroll") for (int k = 0; k < 2; ++k) dst[n][k] = *(const PG8_LAS bf16x8*)(lds + PG8_SB(b, h) + boff + n * 2048 + k * 1024); } while (0)
; #define PG8_SCHED __builtin_amdgcn_sched_barrier(0)
; template <class Epi, class Sched, bool ALIGN_EPI = false, bool SP2 = false>
; __device__ __forceinline__ void gemm_phase(PG8_LAS unsigned char* lds, const Gemm g, const Sched& S, const Epi& E) {
;     ...
;         const bool has_next = S.next(ui + 1, nxt);
;         const char* nA = has_next ? (const char*)g.A + (size_t)nxt.pm * tstep : cA; const char* nB = has_next ? (const char*)g.Bt + (size_t)nxt.pn * tstep : cB;
;         for (int t = 0; t < nt; t += 2) {
;             const bool last = (t == nt - 2);
;             const char* a1 = cA + (size_t)(t + 1) * kstep;
;             const char* a2 = last ? nA : cA + (size_t)(t + 2) * kstep; const char* b2 = last ? nB : cB + (size_t)(t + 2) * kstep;
;             const char* a3 = a2 + kstep; const char* b3 = b2 + kstep;
;             if (last && has_next) S.a_ready(nxt);
;             if constexpr (SP2) {
;             PG8_LDB(B0, 0, 0); PG8_LDB(B1, 0, 1); PG8_SCHED; PG8_LDA(At, 0, 0); PG8_STAGE(PG8_SA(1, 1), a1 + hstep, voffA);
.LBB0_1233:
	s_add_u32 s9, s68, s80
	s_addc_u32 s10, s69, s81
	s_add_u32 s9, s9, 0x100
	s_addc_u32 s10, s10, 0
	s_add_u32 s11, s36, s80
	s_addc_u32 s12, s37, s81
	s_add_i32 s13, 0, 0x10000
	s_cmpk_eq_i32 s80, 0xf00
	s_cselect_b32 s93, s4, s10
	s_cselect_b32 s92, s5, s9
	v_add_u32_e32 v144, s13, v145
	s_cselect_b32 s85, s6, s12
	s_cselect_b32 s84, s7, s11
	s_add_i32 s9, 0, 0x14000
	ds_read_b128 v[152:155], v144
	ds_read_b128 v[156:159], v144 offset:1024
	ds_read_b128 v[160:163], v144 offset:2048
	ds_read_b128 v[164:167], v144 offset:3072
	v_add_u32_e32 v144, s9, v145
	ds_read_b128 v[168:171], v144
	ds_read_b128 v[172:175], v144 offset:1024
	ds_read_b128 v[176:179], v144 offset:2048
	ds_read_b128 v[180:183], v144 offset:3072
	v_lshl_add_u64 v[184:185], v[140:141], 0, s[80:81]
	s_add_i32 m0, s51, 0xc000
	ds_read_b128 v[206:209], v151
	ds_read_b128 v[210:213], v151 offset:1024
	ds_read_b128 v[214:217], v151 offset:2048
	ds_read_b128 v[218:221], v151 offset:3072
	ds_read_b128 v[236:239], v151 offset:4096
	ds_read_b128 v[240:243], v151 offset:5120
	ds_read_b128 v[244:247], v151 offset:6144
	ds_read_b128 v[194:197], v151 offset:7168
	global_load_lds_dwordx4 v[184:185], off
	v_lshl_add_u64 v[184:185], v[142:143], 0, s[80:81]
	s_add_i32 m0, s51, 0xe000
	s_nop 0
	global_load_lds_dwordx4 v[184:185], off
	s_cmp_eq_u32 s101, 0
	s_cbranch_scc1 .Lup_w0_std
	s_waitcnt vmcnt(24)
	s_branch .Lup_w0_done

; #define PG8_STAGE(bufoff, gbase, voff) do { _Pragma("unroll") for (int _i = 0; _i < 2; ++_i) \
;         __builtin_amdgcn_global_load_lds((const unsigned*)((const char*)(gbase) + (voff)[_i]), (PG8_LAS unsigned*)(lds + (bufoff) + ldsw + _i * 8192), 16, 0, 0); } while (0)
; #define PG8_LDA(dst, b, h) do { _Pragma("unroll") for (int m = 0; m < 4; ++m) _Pragma("unroll") for (int k = 0; k < 2; ++k) dst[m][k] = *(const PG8_LAS bf16x8*)(lds + PG8_SA(b, h) + aoff + m * 2048 + k * 1024); } while (0)
; #define PG8_MMA(ai, bj, At, Bt) do { __builtin_amdgcn_s_setprio(1); _Pragma("unroll") for (int m = 0; m < 4; ++m) _Pragma("unroll") for (int n = 0; n < 2; ++n) _Pragma("unroll") for (int k = 0; k < 2; ++k) \
;         acc[ai][bj][m][n] = __builtin_amdgcn_mfma_f32_16x16x32_bf16(Bt[n][k], At[m][k], acc[ai][bj][m][n], 0, 0, 0); __builtin_amdgcn_s_setprio(0); } while (0)
; #define PG8_WAIT_V(n) asm volatile("s_waitcnt vmcnt(" #n ")" ::: "memory")
; #define PG8_WAIT_L(n) asm volatile("s_waitcnt lgkmcnt(" #n ")" ::: "memory")
; #define PG8_BAR __builtin_amdgcn_s_barrier()
; #define PG8_SCHED __builtin_amdgcn_sched_barrier(0)
; template <class Epi, class Sched, bool ALIGN_EPI = false, bool SP2 = false>
; __device__ __forceinline__ void gemm_phase(PG8_LAS unsigned char* lds, const Gemm g, const Sched& S, const Epi& E) {
;     ...
;             PG8_WAIT_V(8); PG8_WAIT_L(0); PG8_BAR; PG8_MMA(0, 0, At, B0); PG8_MMA(0, 1, At, B1); PG8_BAR; PG8_SCHED;
;             PG8_LDA(At, 0, 1); PG8_STAGE(PG8_SB(0, 0), b2, voffB); PG8_STAGE(PG8_SB(0, 1), b2 + hstepB, voffB); PG8_STAGE(PG8_SA(0, 0), a2, voffA);
.Lup_w0_done:
	s_waitcnt lgkmcnt(0)
	s_barrier
	s_setprio 1
	s_waitcnt lgkmcnt(0)
	v_mfma_f32_16x16x32_bf16 v[126:129], v[152:155], v[206:209], v[126:129]
	v_mfma_f32_16x16x32_bf16 v[122:125], v[160:163], v[206:209], v[122:125]
	v_mfma_f32_16x16x32_bf16 v[118:121], v[152:155], v[214:217], v[118:121]
	v_mfma_f32_16x16x32_bf16 v[114:117], v[160:163], v[214:217], v[114:117]
	v_mfma_f32_16x16x32_bf16 v[110:113], v[152:155], v[236:239], v[110:113]
	v_mfma_f32_16x16x32_bf16 v[106:109], v[160:163], v[236:239], v[106:109]
	v_mfma_f32_16x16x32_bf16 v[102:105], v[152:155], v[244:247], v[102:105]
	v_mfma_f32_16x16x32_bf16 v[98:101], v[160:163], v[244:247], v[98:101]
	v_mfma_f32_16x16x32_bf16 v[126:129], v[156:159], v[210:213], v[126:129]
	v_mfma_f32_16x16x32_bf16 v[122:125], v[164:167], v[210:213], v[122:125]
	v_mfma_f32_16x16x32_bf16 v[118:121], v[156:159], v[218:221], v[118:121]
	v_mfma_f32_16x16x32_bf16 v[114:117], v[164:167], v[218:221], v[114:117]
	v_mfma_f32_16x16x32_bf16 v[110:113], v[156:159], v[240:243], v[110:113]
	v_mfma_f32_16x16x32_bf16 v[106:109], v[164:167], v[240:243], v[106:109]
	v_mfma_f32_16x16x32_bf16 v[102:105], v[156:159], v[194:197], v[102:105]
	v_mfma_f32_16x16x32_bf16 v[98:101], v[164:167], v[194:197], v[98:101]
	s_setprio 0
	s_setprio 1
	v_mfma_f32_16x16x32_bf16 v[94:97], v[168:171], v[206:209], v[94:97]
	v_mfma_f32_16x16x32_bf16 v[90:93], v[176:179], v[206:209], v[90:93]
	v_mfma_f32_16x16x32_bf16 v[86:89], v[168:171], v[214:217], v[86:89]
	v_mfma_f32_16x16x32_bf16 v[82:85], v[176:179], v[214:217], v[82:85]
	v_mfma_f32_16x16x32_bf16 v[78:81], v[168:171], v[236:239], v[78:81]
	v_mfma_f32_16x16x32_bf16 v[74:77], v[176:179], v[236:239], v[74:77]
	v_mfma_f32_16x16x32_bf16 v[70:73], v[168:171], v[244:247], v[70:73]
	v_mfma_f32_16x16x32_bf16 v[66:69], v[176:179], v[244:247], v[66:69]
	v_mfma_f32_16x16x32_bf16 v[94:97], v[172:175], v[210:213], v[94:97]
	v_mfma_f32_16x16x32_bf16 v[90:93], v[180:183], v[210:213], v[90:93]
	v_mfma_f32_16x16x32_bf16 v[86:89], v[172:175], v[218:221], v[86:89]
	v_mfma_f32_16x16x32_bf16 v[82:85], v[180:183], v[218:221], v[82:85]
	v_mfma_f32_16x16x32_bf16 v[78:81], v[172:175], v[240:243], v[78:81]
	v_mfma_f32_16x16x32_bf16 v[74:77], v[180:183], v[240:243], v[74:77]
	v_mfma_f32_16x16x32_bf16 v[70:73], v[172:175], v[194:197], v[70:73]
	v_mfma_f32_16x16x32_bf16 v[66:69], v[180:183], v[194:197], v[66:69]
	s_setprio 0
	s_barrier
	s_add_i32 s10, s13, s42
	v_lshl_add_u64 v[184:185], s[84:85], 0, v[130:131]
	s_mov_b32 m0, s10
	ds_read_b128 v[194:197], v151 offset:16384
	ds_read_b128 v[206:209], v151 offset:17408
	ds_read_b128 v[210:213], v151 offset:18432
	ds_read_b128 v[214:217], v151 offset:19456
	ds_read_b128 v[218:221], v151 offset:20480
	ds_read_b128 v[236:239], v151 offset:21504
	ds_read_b128 v[240:243], v151 offset:22528
	ds_read_b128 v[244:247], v151 offset:23552
	global_load_lds_dwordx4 v[184:185], off
	s_add_i32 m0, s10, 0x2000
	s_add_u32 s10, s84, 0x20000
	v_lshl_add_u64 v[198:199], s[84:85], 0, v[134:135]
	s_addc_u32 s11, s85, 0
	s_add_i32 s9, s9, s42
	global_load_lds_dwordx4 v[198:199], off
	v_lshl_add_u64 v[222:223], s[10:11], 0, v[130:131]
	s_mov_b32 m0, s9
	v_lshl_add_u64 v[234:235], s[92:93], 0, v[132:133]
	global_load_lds_dwordx4 v[222:223], off
	v_lshl_add_u64 v[222:223], s[10:11], 0, v[134:135]
	s_add_i32 m0, s9, 0x2000
	s_nop 0
	global_load_lds_dwordx4 v[222:223], off
	v_lshl_add_u64 v[222:223], s[92:93], 0, v[190:191]
	s_mov_b32 m0, s51
	s_nop 0
	global_load_lds_dwordx4 v[222:223], off
	s_mov_b32 m0, s67
	s_nop 0
	global_load_lds_dwordx4 v[234:235], off
	s_cmp_eq_u32 s101, 0
	s_cbranch_scc1 .Lup_w1_std
	s_waitcnt vmcnt(24)
	s_mov_b32 s101, 0
	s_branch .Lup_w1_done

; #define PG8_STAGE(bufoff, gbase, voff) do { _Pragma("unroll") for (int _i = 0; _i < 2; ++_i) \
;         __builtin_amdgcn_global_load_lds((const unsigned*)((const char*)(gbase) + (voff)[_i]), (PG8_LAS unsigned*)(lds + (bufoff) + ldsw + _i * 8192), 16, 0, 0); } while (0)
; #define PG8_LDA(dst, b, h) do { _Pragma("unroll") for (int m = 0; m < 4; ++m) _Pragma("unroll") for (int k = 0; k < 2; ++k) dst[m][k] = *(const PG8_LAS bf16x8*)(lds + PG8_SA(b, h) + aoff + m * 2048 + k * 1024); } while (0)
; #define PG8_LDB(dst, b, h) do { _Pragma("unroll") for (int n = 0; n < 2; ++n) _Pragma("unroll") for (int k = 0; k < 2; ++k) dst[n][k] = *(const PG8_LAS bf16x8*)(lds + PG8_SB(b, h) + boff + n * 2048 + k * 1024); } while (0)
; #define PG8_MMA(ai, bj, At, Bt) do { __builtin_amdgcn_s_setprio(1); _Pragma("unroll") for (int m = 0; m < 4; ++m) _Pragma("unroll") for (int n = 0; n < 2; ++n) _Pragma("unroll") for (int k = 0; k < 2; ++k) \
;         acc[ai][bj][m][n] = __builtin_amdgcn_mfma_f32_16x16x32_bf16(Bt[n][k], At[m][k], acc[ai][bj][m][n], 0, 0, 0); __builtin_amdgcn_s_setprio(0); } while (0)
; #define PG8_WAIT_V(n) asm volatile("s_waitcnt vmcnt(" #n ")" ::: "memory")
; #define PG8_WAIT_L(n) asm volatile("s_waitcnt lgkmcnt(" #n ")" ::: "memory")
; #define PG8_BAR __builtin_amdgcn_s_barrier()
; #define PG8_SCHED __builtin_amdgcn_sched_barrier(0)
; template <class Epi, class Sched, bool ALIGN_EPI = false, bool SP2 = false>
; __device__ __forceinline__ void gemm_phase(PG8_LAS unsigned char* lds, const Gemm g, const Sched& S, const Epi& E) {
;     ...
;             PG8_WAIT_V(8); PG8_WAIT_L(0); PG8_BAR; PG8_MMA(1, 0, At, B0); PG8_MMA(1, 1, At, B1); PG8_BAR; PG8_SCHED;
;             PG8_LDB(B0, 1, 0); PG8_LDB(B1, 1, 1); PG8_SCHED; PG8_LDA(At, 1, 0); PG8_STAGE(PG8_SA(0, 1), a2 + hstep, voffA);
;             PG8_WAIT_V(8); PG8_WAIT_L(0); PG8_BAR; PG8_MMA(0, 0, At, B0); PG8_MMA(0, 1, At, B1); PG8_BAR; PG8_SCHED;
.Lup_w1_done:
	s_waitcnt lgkmcnt(0)
	s_barrier
	s_setprio 1
	s_waitcnt lgkmcnt(0)
	v_mfma_f32_16x16x32_bf16 v[62:65], v[152:155], v[194:197], v[62:65]
	v_mfma_f32_16x16x32_bf16 v[58:61], v[160:163], v[194:197], v[58:61]
	v_mfma_f32_16x16x32_bf16 v[54:57], v[152:155], v[210:213], v[54:57]
	v_mfma_f32_16x16x32_bf16 v[50:53], v[160:163], v[210:213], v[50:53]
	v_mfma_f32_16x16x32_bf16 v[46:49], v[152:155], v[218:221], v[46:49]
	v_mfma_f32_16x16x32_bf16 v[42:45], v[160:163], v[218:221], v[42:45]
	v_mfma_f32_16x16x32_bf16 v[38:41], v[152:155], v[240:243], v[38:41]
	v_mfma_f32_16x16x32_bf16 v[34:37], v[160:163], v[240:243], v[34:37]
	v_mfma_f32_16x16x32_bf16 v[62:65], v[156:159], v[206:209], v[62:65]
	v_mfma_f32_16x16x32_bf16 v[58:61], v[164:167], v[206:209], v[58:61]
	v_mfma_f32_16x16x32_bf16 v[54:57], v[156:159], v[214:217], v[54:57]
	v_mfma_f32_16x16x32_bf16 v[50:53], v[164:167], v[214:217], v[50:53]
	v_mfma_f32_16x16x32_bf16 v[46:49], v[156:159], v[236:239], v[46:49]
	v_mfma_f32_16x16x32_bf16 v[42:45], v[164:167], v[236:239], v[42:45]
	v_mfma_f32_16x16x32_bf16 v[38:41], v[156:159], v[244:247], v[38:41]
	v_mfma_f32_16x16x32_bf16 v[34:37], v[164:167], v[244:247], v[34:37]
	s_setprio 0
	s_setprio 1
	v_mfma_f32_16x16x32_bf16 v[30:33], v[168:171], v[194:197], v[30:33]
	v_mfma_f32_16x16x32_bf16 v[26:29], v[176:179], v[194:197], v[26:29]
	v_mfma_f32_16x16x32_bf16 v[22:25], v[168:171], v[210:213], v[22:25]
	v_mfma_f32_16x16x32_bf16 v[18:21], v[176:179], v[210:213], v[18:21]
	v_mfma_f32_16x16x32_bf16 v[14:17], v[168:171], v[218:221], v[14:17]
	v_mfma_f32_16x16x32_bf16 v[10:13], v[176:179], v[218:221], v[10:13]
	v_mfma_f32_16x16x32_bf16 v[6:9], v[168:171], v[240:243], v[6:9]
	v_mfma_f32_16x16x32_bf16 v[2:5], v[176:179], v[240:243], v[2:5]
	v_mfma_f32_16x16x32_bf16 v[30:33], v[172:175], v[206:209], v[30:33]
	v_mfma_f32_16x16x32_bf16 v[26:29], v[180:183], v[206:209], v[26:29]
	v_mfma_f32_16x16x32_bf16 v[22:25], v[172:175], v[214:217], v[22:25]
	v_mfma_f32_16x16x32_bf16 v[18:21], v[180:183], v[214:217], v[18:21]
	v_mfma_f32_16x16x32_bf16 v[14:17], v[172:175], v[236:239], v[14:17]
	v_mfma_f32_16x16x32_bf16 v[10:13], v[180:183], v[236:239], v[10:13]
	v_mfma_f32_16x16x32_bf16 v[6:9], v[172:175], v[244:247], v[6:9]
	v_mfma_f32_16x16x32_bf16 v[2:5], v[180:183], v[244:247], v[2:5]
	s_setprio 0
	s_barrier
	s_add_i32 s9, 0, 0x18000
	v_add_u32_e32 v144, s9, v145
	s_add_i32 s12, 0, 0x1c000
	ds_read_b128 v[152:155], v144
	ds_read_b128 v[156:159], v144 offset:1024
	ds_read_b128 v[160:163], v144 offset:2048
	ds_read_b128 v[164:167], v144 offset:3072
	v_add_u32_e32 v144, s12, v145
	ds_read_b128 v[168:171], v144
	ds_read_b128 v[172:175], v144 offset:1024
	ds_read_b128 v[176:179], v144 offset:2048
	ds_read_b128 v[180:183], v144 offset:3072
	s_add_u32 s10, s92, 0x80000
	s_addc_u32 s11, s93, 0
	s_mov_b32 m0, s74
	v_lshl_add_u64 v[186:187], s[10:11], 0, v[190:191]
	ds_read_b128 v[194:197], v151 offset:32768
	ds_read_b128 v[206:209], v151 offset:33792
	ds_read_b128 v[210:213], v151 offset:34816
	ds_read_b128 v[214:217], v151 offset:35840
	ds_read_b128 v[218:221], v151 offset:36864
	ds_read_b128 v[236:239], v151 offset:37888
	ds_read_b128 v[240:243], v151 offset:38912
	ds_read_b128 v[244:247], v151 offset:39936
	global_load_lds_dwordx4 v[186:187], off
	v_lshl_add_u64 v[186:187], s[10:11], 0, v[132:133]
	s_mov_b32 m0, s75
	s_nop 0
	global_load_lds_dwordx4 v[186:187], off
	s_waitcnt vmcnt(8)
	s_waitcnt lgkmcnt(0)
	s_barrier
	s_setprio 1
	s_waitcnt lgkmcnt(0)
	v_mfma_f32_16x16x32_bf16 v[126:129], v[152:155], v[194:197], v[126:129]
	v_mfma_f32_16x16x32_bf16 v[122:125], v[160:163], v[194:197], v[122:125]
	v_mfma_f32_16x16x32_bf16 v[118:121], v[152:155], v[210:213], v[118:121]
	v_mfma_f32_16x16x32_bf16 v[114:117], v[160:163], v[210:213], v[114:117]
	v_mfma_f32_16x16x32_bf16 v[110:113], v[152:155], v[218:221], v[110:113]
	v_mfma_f32_16x16x32_bf16 v[106:109], v[160:163], v[218:221], v[106:109]
	v_mfma_f32_16x16x32_bf16 v[102:105], v[152:155], v[240:243], v[102:105]
	v_mfma_f32_16x16x32_bf16 v[98:101], v[160:163], v[240:243], v[98:101]
	v_mfma_f32_16x16x32_bf16 v[126:129], v[156:159], v[206:209], v[126:129]
	v_mfma_f32_16x16x32_bf16 v[122:125], v[164:167], v[206:209], v[122:125]
	v_mfma_f32_16x16x32_bf16 v[118:121], v[156:159], v[214:217], v[118:121]
	v_mfma_f32_16x16x32_bf16 v[114:117], v[164:167], v[214:217], v[114:117]
	v_mfma_f32_16x16x32_bf16 v[110:113], v[156:159], v[236:239], v[110:113]
	v_mfma_f32_16x16x32_bf16 v[106:109], v[164:167], v[236:239], v[106:109]
	v_mfma_f32_16x16x32_bf16 v[102:105], v[156:159], v[244:247], v[102:105]
	v_mfma_f32_16x16x32_bf16 v[98:101], v[164:167], v[244:247], v[98:101]
	s_setprio 0
	s_setprio 1
	v_mfma_f32_16x16x32_bf16 v[94:97], v[168:171], v[194:197], v[94:97]
	v_mfma_f32_16x16x32_bf16 v[90:93], v[176:179], v[194:197], v[90:93]
	v_mfma_f32_16x16x32_bf16 v[86:89], v[168:171], v[210:213], v[86:89]
	v_mfma_f32_16x16x32_bf16 v[82:85], v[176:179], v[210:213], v[82:85]
	v_mfma_f32_16x16x32_bf16 v[78:81], v[168:171], v[218:221], v[78:81]
	v_mfma_f32_16x16x32_bf16 v[74:77], v[176:179], v[218:221], v[74:77]
	v_mfma_f32_16x16x32_bf16 v[70:73], v[168:171], v[240:243], v[70:73]
	v_mfma_f32_16x16x32_bf16 v[66:69], v[176:179], v[240:243], v[66:69]
	v_mfma_f32_16x16x32_bf16 v[94:97], v[172:175], v[206:209], v[94:97]
	v_mfma_f32_16x16x32_bf16 v[90:93], v[180:183], v[206:209], v[90:93]
	v_mfma_f32_16x16x32_bf16 v[86:89], v[172:175], v[214:217], v[86:89]
	v_mfma_f32_16x16x32_bf16 v[82:85], v[180:183], v[214:217], v[82:85]
	v_mfma_f32_16x16x32_bf16 v[78:81], v[172:175], v[236:239], v[78:81]
	v_mfma_f32_16x16x32_bf16 v[74:77], v[180:183], v[236:239], v[74:77]
	v_mfma_f32_16x16x32_bf16 v[70:73], v[172:175], v[244:247], v[70:73]
	v_mfma_f32_16x16x32_bf16 v[66:69], v[180:183], v[244:247], v[66:69]
	s_setprio 0
	s_barrier
; #define PG8_STAGE(bufoff, gbase, voff) do { _Pragma("unroll") for (int _i = 0; _i < 2; ++_i) \
;         __builtin_amdgcn_global_load_lds((const unsigned*)((const char*)(gbase) + (voff)[_i]), (PG8_LAS unsigned*)(lds + (bufoff) + ldsw + _i * 8192), 16, 0, 0); } while (0)
; #define PG8_LDA(dst, b, h) do { _Pragma("unroll") for (int m = 0; m < 4; ++m) _Pragma("unroll") for (int k = 0; k < 2; ++k) dst[m][k] = *(const PG8_LAS bf16x8*)(lds + PG8_SA(b, h) + aoff + m * 2048 + k * 1024); } while (0)
; #define PG8_MMA(ai, bj, At, Bt) do { __builtin_amdgcn_s_setprio(1); _Pragma("unroll") for (int m = 0; m < 4; ++m) _Pragma("unroll") for (int n = 0; n < 2; ++n) _Pragma("unroll") for (int k = 0; k < 2; ++k) \
;         acc[ai][bj][m][n] = __builtin_amdgcn_mfma_f32_16x16x32_bf16(Bt[n][k], At[m][k], acc[ai][bj][m][n], 0, 0, 0); __builtin_amdgcn_s_setprio(0); } while (0)
; #define PG8_WAIT_V(n) asm volatile("s_waitcnt vmcnt(" #n ")" ::: "memory")
; #define PG8_WAIT_L(n) asm volatile("s_waitcnt lgkmcnt(" #n ")" ::: "memory")
; #define PG8_BAR __builtin_amdgcn_s_barrier()
; #define PG8_SCHED __builtin_amdgcn_sched_barrier(0)
; template <class Epi, class Sched, bool ALIGN_EPI = false, bool SP2 = false>
; __device__ __forceinline__ void gemm_phase(PG8_LAS unsigned char* lds, const Gemm g, const Sched& S, const Epi& E) {
;     ...
;             PG8_LDA(At, 1, 1); PG8_STAGE(PG8_SB(1, 0), b3, voffB); PG8_STAGE(PG8_SB(1, 1), b3 + hstepB, voffB); PG8_STAGE(PG8_SA(1, 0), a3, voffA);
;             PG8_WAIT_V(8); PG8_WAIT_L(0); PG8_BAR; PG8_MMA(1, 0, At, B0); PG8_MMA(1, 1, At, B1); PG8_BAR; PG8_SCHED;
;     ...
;         if constexpr (ALIGN_EPI) { if (wr == 0) PG8_BAR; }
	s_add_i32 s9, s9, s42
	v_lshl_add_u64 v[184:185], v[184:185], 0, s[60:61]
	s_mov_b32 m0, s9
	ds_read_b128 v[194:197], v151 offset:49152
	ds_read_b128 v[206:209], v151 offset:50176
	ds_read_b128 v[210:213], v151 offset:51200
	ds_read_b128 v[214:217], v151 offset:52224
	ds_read_b128 v[218:221], v151 offset:53248
	ds_read_b128 v[236:239], v151 offset:54272
	ds_read_b128 v[240:243], v151 offset:55296
	ds_read_b128 v[244:247], v151 offset:56320
	global_load_lds_dwordx4 v[184:185], off
	s_add_i32 m0, s9, 0x2000
	s_add_u32 s10, s84, 0x20080
	v_lshl_add_u64 v[184:185], v[198:199], 0, s[60:61]
	s_addc_u32 s11, s85, 0
	s_add_i32 s9, s12, s42
	global_load_lds_dwordx4 v[184:185], off
	v_lshl_add_u64 v[184:185], s[10:11], 0, v[130:131]
	s_mov_b32 m0, s9
	s_nop 0
	global_load_lds_dwordx4 v[184:185], off
	v_lshl_add_u64 v[184:185], s[10:11], 0, v[134:135]
	s_add_i32 m0, s9, 0x2000
	s_nop 0
	global_load_lds_dwordx4 v[184:185], off
	v_lshl_add_u64 v[184:185], v[222:223], 0, s[60:61]
	s_mov_b32 m0, s82
	s_nop 0
	global_load_lds_dwordx4 v[184:185], off
	v_lshl_add_u64 v[184:185], v[234:235], 0, s[60:61]
	s_mov_b32 m0, s86
	s_nop 0
	global_load_lds_dwordx4 v[184:185], off
	s_waitcnt vmcnt(8)
	s_waitcnt lgkmcnt(0)
	s_barrier
	s_setprio 1
	s_waitcnt lgkmcnt(0)
	v_mfma_f32_16x16x32_bf16 v[62:65], v[152:155], v[194:197], v[62:65]
	v_mfma_f32_16x16x32_bf16 v[58:61], v[160:163], v[194:197], v[58:61]
	v_mfma_f32_16x16x32_bf16 v[54:57], v[152:155], v[210:213], v[54:57]
	v_mfma_f32_16x16x32_bf16 v[50:53], v[160:163], v[210:213], v[50:53]
	v_mfma_f32_16x16x32_bf16 v[46:49], v[152:155], v[218:221], v[46:49]
	v_mfma_f32_16x16x32_bf16 v[42:45], v[160:163], v[218:221], v[42:45]
	v_mfma_f32_16x16x32_bf16 v[38:41], v[152:155], v[240:243], v[38:41]
	v_mfma_f32_16x16x32_bf16 v[34:37], v[160:163], v[240:243], v[34:37]
	v_mfma_f32_16x16x32_bf16 v[62:65], v[156:159], v[206:209], v[62:65]
	v_mfma_f32_16x16x32_bf16 v[58:61], v[164:167], v[206:209], v[58:61]
	v_mfma_f32_16x16x32_bf16 v[54:57], v[156:159], v[214:217], v[54:57]
	v_mfma_f32_16x16x32_bf16 v[50:53], v[164:167], v[214:217], v[50:53]
	v_mfma_f32_16x16x32_bf16 v[46:49], v[156:159], v[236:239], v[46:49]
	v_mfma_f32_16x16x32_bf16 v[42:45], v[164:167], v[236:239], v[42:45]
	v_mfma_f32_16x16x32_bf16 v[38:41], v[156:159], v[244:247], v[38:41]
	v_mfma_f32_16x16x32_bf16 v[34:37], v[164:167], v[244:247], v[34:37]
	s_setprio 0
	s_setprio 1
	v_mfma_f32_16x16x32_bf16 v[30:33], v[168:171], v[194:197], v[30:33]
	v_mfma_f32_16x16x32_bf16 v[26:29], v[176:179], v[194:197], v[26:29]
	v_mfma_f32_16x16x32_bf16 v[22:25], v[168:171], v[210:213], v[22:25]
	v_mfma_f32_16x16x32_bf16 v[18:21], v[176:179], v[210:213], v[18:21]
	v_mfma_f32_16x16x32_bf16 v[14:17], v[168:171], v[218:221], v[14:17]
	v_mfma_f32_16x16x32_bf16 v[10:13], v[176:179], v[218:221], v[10:13]
	v_mfma_f32_16x16x32_bf16 v[6:9], v[168:171], v[240:243], v[6:9]
	v_mfma_f32_16x16x32_bf16 v[2:5], v[176:179], v[240:243], v[2:5]
	v_mfma_f32_16x16x32_bf16 v[30:33], v[172:175], v[206:209], v[30:33]
	v_mfma_f32_16x16x32_bf16 v[26:29], v[180:183], v[206:209], v[26:29]
	v_mfma_f32_16x16x32_bf16 v[22:25], v[172:175], v[214:217], v[22:25]
	v_mfma_f32_16x16x32_bf16 v[18:21], v[180:183], v[214:217], v[18:21]
	v_mfma_f32_16x16x32_bf16 v[14:17], v[172:175], v[236:239], v[14:17]
	v_mfma_f32_16x16x32_bf16 v[10:13], v[180:183], v[236:239], v[10:13]
	v_mfma_f32_16x16x32_bf16 v[6:9], v[172:175], v[244:247], v[6:9]
	v_mfma_f32_16x16x32_bf16 v[2:5], v[180:183], v[244:247], v[2:5]
	s_setprio 0
	s_barrier
	s_add_i32 s8, s8, 2
	s_add_u32 s80, s80, 0x100
	s_addc_u32 s81, s81, 0
	s_cmp_gt_u32 s8, 29
	s_cbranch_scc0 .LBB0_1233
	s_and_b64 vcc, exec, s[62:63]
	s_cbranch_vccz .LBB0_1236
	s_barrier
